# P5 epilogue: 256 dead zero-inits before full-row DPP moves removed (hazard padding kept)
# baseline (speedup 1.0000x reference)
; __device__ __forceinline__ float row_rstd(const float* ssp, int row, int fq) {
;     const f32x4 a = *(const f32x4*)(ssp + (size_t)row * 32 + 8 * fq), b = *(const f32x4*)(ssp + (size_t)row * 32 + 8 * fq + 4);
;     float s = ((a[0] + a[1]) + (a[2] + a[3])) + ((b[0] + b[1]) + (b[2] + b[3]));
;     s += __shfl_xor(s, 16); s += __shfl_xor(s, 32);
;     return __builtin_amdgcn_rsqf(s * (1.0f / 2048.0f) + 1e-6f);
; }
;     __device__ __forceinline__ void operator()(f32x4 (&acc)[2][2][4][2], const Unit& u, int wr, int wc, int fr, int fq) const {
;         const int row0 = u.pm * BM + wr * 64 + fr;
; #pragma unroll
;         for (int ai = 0; ai < 2; ++ai)
; #pragma unroll
;             for (int m = 0; m < 4; ++m) { const float rstd = row_rstd(ss, row0 + ai * HALF + m * 16, fq);
; #pragma unroll
;                 for (int bj = 0; bj < 2; ++bj) { acc[ai][bj][m][0] *= rstd; acc[ai][bj][m][1] *= rstd; } }
.LBB0_755:
	s_waitcnt vmcnt(14)
	v_add_f32_e32 v174, v174, v175
	v_add_f32_e32 v176, v176, v177
	v_add_f32_e32 v178, v178, v179
	v_add_f32_e32 v180, v180, v181
	v_add_f32_e32 v174, v174, v176
	v_add_f32_e32 v178, v178, v180
	v_add_f32_e32 v130, v174, v178
	s_waitcnt vmcnt(12)
	v_add_f32_e32 v182, v182, v183
	v_add_f32_e32 v184, v184, v185
	v_add_f32_e32 v186, v186, v187
	v_add_f32_e32 v188, v188, v189
	v_add_f32_e32 v182, v182, v184
	v_add_f32_e32 v186, v186, v188
	v_add_f32_e32 v132, v182, v186
	s_waitcnt vmcnt(10)
	v_add_f32_e32 v190, v190, v191
	v_add_f32_e32 v192, v192, v193
	v_add_f32_e32 v194, v194, v195
	v_add_f32_e32 v196, v196, v197
	v_add_f32_e32 v190, v190, v192
	v_add_f32_e32 v194, v194, v196
	v_add_f32_e32 v134, v190, v194
	s_waitcnt vmcnt(8)
	v_add_f32_e32 v198, v198, v199
	v_add_f32_e32 v200, v200, v201
	v_add_f32_e32 v202, v202, v203
	v_add_f32_e32 v204, v204, v205
	v_add_f32_e32 v198, v198, v200
	v_add_f32_e32 v202, v202, v204
	v_add_f32_e32 v136, v198, v202
	s_waitcnt vmcnt(6)
	v_add_f32_e32 v206, v206, v207
	v_add_f32_e32 v208, v208, v209
	v_add_f32_e32 v210, v210, v211
	v_add_f32_e32 v212, v212, v213
	v_add_f32_e32 v206, v206, v208
	v_add_f32_e32 v210, v210, v212
	v_add_f32_e32 v138, v206, v210
	s_waitcnt vmcnt(4)
	v_add_f32_e32 v214, v214, v215
	v_add_f32_e32 v216, v216, v217
	v_add_f32_e32 v218, v218, v219
	v_add_f32_e32 v220, v220, v221
	v_add_f32_e32 v214, v214, v216
	v_add_f32_e32 v218, v218, v220
	v_add_f32_e32 v140, v214, v218
	s_waitcnt vmcnt(2)
	v_add_f32_e32 v222, v222, v223
	v_add_f32_e32 v224, v224, v225
	v_add_f32_e32 v226, v226, v227
	v_add_f32_e32 v228, v228, v229
	v_add_f32_e32 v222, v222, v224
	v_add_f32_e32 v226, v226, v228
	v_add_f32_e32 v142, v222, v226
	s_waitcnt vmcnt(0)
	v_add_f32_e32 v230, v230, v231
	v_add_f32_e32 v232, v232, v233
	v_add_f32_e32 v234, v234, v235
	v_add_f32_e32 v236, v236, v237
	v_add_f32_e32 v230, v230, v232
	v_add_f32_e32 v234, v234, v236
	v_add_f32_e32 v144, v230, v234
	ds_bpermute_b32 v174, v238, v130
	ds_bpermute_b32 v175, v238, v132
	ds_bpermute_b32 v176, v238, v134
	ds_bpermute_b32 v177, v238, v136
	ds_bpermute_b32 v178, v238, v138
	ds_bpermute_b32 v179, v238, v140
	ds_bpermute_b32 v180, v238, v142
	ds_bpermute_b32 v181, v238, v144
	s_waitcnt lgkmcnt(0)
	v_add_f32_e32 v130, v130, v174
	v_add_f32_e32 v132, v132, v175
	v_add_f32_e32 v134, v134, v176
	v_add_f32_e32 v136, v136, v177
	v_add_f32_e32 v138, v138, v178
	v_add_f32_e32 v140, v140, v179
	v_add_f32_e32 v142, v142, v180
	v_add_f32_e32 v144, v144, v181
	ds_bpermute_b32 v174, v239, v130
	ds_bpermute_b32 v175, v239, v132
	ds_bpermute_b32 v176, v239, v134
	ds_bpermute_b32 v177, v239, v136
	ds_bpermute_b32 v178, v239, v138
	ds_bpermute_b32 v179, v239, v140
	ds_bpermute_b32 v180, v239, v142
	ds_bpermute_b32 v181, v239, v144
	s_waitcnt lgkmcnt(0)
	v_add_f32_e32 v130, v130, v174
	v_add_f32_e32 v132, v132, v175
	v_add_f32_e32 v134, v134, v176
	v_add_f32_e32 v136, v136, v177
	v_add_f32_e32 v138, v138, v178
	v_add_f32_e32 v140, v140, v179
	v_add_f32_e32 v142, v142, v180
	v_add_f32_e32 v144, v144, v181
	v_fmamk_f32 v130, v130, 0x3a000000, v243
	v_fmamk_f32 v132, v132, 0x3a000000, v243
	v_fmamk_f32 v134, v134, 0x3a000000, v243
	v_fmamk_f32 v136, v136, 0x3a000000, v243
	v_fmamk_f32 v138, v138, 0x3a000000, v243
	v_fmamk_f32 v140, v140, 0x3a000000, v243
	v_fmamk_f32 v142, v142, 0x3a000000, v243
	v_fmamk_f32 v144, v144, 0x3a000000, v243
	v_rsq_f32_e32 v130, v130
	v_rsq_f32_e32 v132, v132
	v_rsq_f32_e32 v134, v134
	v_rsq_f32_e32 v136, v136
	v_rsq_f32_e32 v138, v138
	v_rsq_f32_e32 v140, v140
	v_rsq_f32_e32 v142, v142
	v_rsq_f32_e32 v144, v144
	s_nop 0
	v_pk_mul_f32 v[126:127], v[126:127], v[130:131] op_sel_hi:[1,0]
	v_pk_mul_f32 v[128:129], v[128:129], v[130:131] op_sel_hi:[1,0]
	v_pk_mul_f32 v[62:63], v[62:63], v[130:131] op_sel_hi:[1,0]
	v_pk_mul_f32 v[64:65], v[64:65], v[130:131] op_sel_hi:[1,0]
	v_pk_mul_f32 v[122:123], v[122:123], v[130:131] op_sel_hi:[1,0]
	v_pk_mul_f32 v[124:125], v[124:125], v[130:131] op_sel_hi:[1,0]
	v_pk_mul_f32 v[54:55], v[54:55], v[130:131] op_sel_hi:[1,0]
	v_pk_mul_f32 v[56:57], v[56:57], v[130:131] op_sel_hi:[1,0]
	v_pk_mul_f32 v[118:119], v[118:119], v[132:133] op_sel_hi:[1,0]
	v_pk_mul_f32 v[120:121], v[120:121], v[132:133] op_sel_hi:[1,0]
	v_pk_mul_f32 v[58:59], v[58:59], v[132:133] op_sel_hi:[1,0]
	v_pk_mul_f32 v[60:61], v[60:61], v[132:133] op_sel_hi:[1,0]
	v_pk_mul_f32 v[114:115], v[114:115], v[132:133] op_sel_hi:[1,0]
	v_pk_mul_f32 v[116:117], v[116:117], v[132:133] op_sel_hi:[1,0]
	v_pk_mul_f32 v[50:51], v[50:51], v[132:133] op_sel_hi:[1,0]
	v_pk_mul_f32 v[52:53], v[52:53], v[132:133] op_sel_hi:[1,0]
	v_pk_mul_f32 v[110:111], v[110:111], v[134:135] op_sel_hi:[1,0]
	v_pk_mul_f32 v[112:113], v[112:113], v[134:135] op_sel_hi:[1,0]
	v_pk_mul_f32 v[46:47], v[46:47], v[134:135] op_sel_hi:[1,0]
	v_pk_mul_f32 v[48:49], v[48:49], v[134:135] op_sel_hi:[1,0]
	v_pk_mul_f32 v[102:103], v[102:103], v[134:135] op_sel_hi:[1,0]
	v_pk_mul_f32 v[104:105], v[104:105], v[134:135] op_sel_hi:[1,0]
	v_pk_mul_f32 v[38:39], v[38:39], v[134:135] op_sel_hi:[1,0]
	v_pk_mul_f32 v[40:41], v[40:41], v[134:135] op_sel_hi:[1,0]
	v_pk_mul_f32 v[106:107], v[106:107], v[136:137] op_sel_hi:[1,0]
	v_pk_mul_f32 v[108:109], v[108:109], v[136:137] op_sel_hi:[1,0]
	v_pk_mul_f32 v[42:43], v[42:43], v[136:137] op_sel_hi:[1,0]
	v_pk_mul_f32 v[44:45], v[44:45], v[136:137] op_sel_hi:[1,0]
	v_pk_mul_f32 v[98:99], v[98:99], v[136:137] op_sel_hi:[1,0]
	v_pk_mul_f32 v[100:101], v[100:101], v[136:137] op_sel_hi:[1,0]
	v_pk_mul_f32 v[34:35], v[34:35], v[136:137] op_sel_hi:[1,0]
	v_pk_mul_f32 v[36:37], v[36:37], v[136:137] op_sel_hi:[1,0]
;     __device__ __forceinline__ void operator()(f32x4 (&acc)[2][2][4][2], const Unit& u, int wr, int wc, int fr, int fq) const {
;     ...
;             for (int m = 0; m < 4; ++m) { const float rstd = row_rstd(ss, row0 + ai * HALF + m * 16, fq);
; #pragma unroll
;                 for (int bj = 0; bj < 2; ++bj) { acc[ai][bj][m][0] *= rstd; acc[ai][bj][m][1] *= rstd; } }
; #pragma unroll
;         for (int n = 0; n < 2; ++n) {
;             const int j4 = u.pn * 128 + wc * 32 + 8 * fq + 4 * n;
;             f32x4 kc[2][3], bc[2];
; #pragma unroll
;             for (int bj = 0; bj < 2; ++bj) { bc[bj] = *(const f32x4*)(cb + bj * FF + j4);
; #pragma unroll
;                 for (int w = 0; w < 3; ++w) kc[bj][w] = *(const f32x4*)(ck + w * NUP + bj * FF + j4); }
; #pragma unroll
;             for (int ai = 0; ai < 2; ++ai) {
;                 const int grp = u.pm * 4 + ai * 2 + wr;
; #pragma unroll
;                 for (int m = 0; m < 4; ++m) {
;                     f32x4 cv[2];
; #pragma unroll
;                     for (int bj = 0; bj < 2; ++bj) {
;                         const f32x4 cur = acc[ai][bj][m][n], lo = acc[ai][bj][m > 0 ? m - 1 : 0][n], hi = acc[ai][bj][m < 3 ? m + 1 : 3][n];
;                         f32x4 pv, nv;
; #pragma unroll
;                         for (int idx = 0; idx < 4; ++idx) {
;                             const float y = (fr == 15) ? lo[idx] : cur[idx], z = (fr == 0) ? hi[idx] : cur[idx];
;                             pv[idx] = __int_as_float(__builtin_amdgcn_update_dpp(0, __float_as_int(y), 0x121, 0xf, 0xf, false));
;                             nv[idx] = __int_as_float(__builtin_amdgcn_update_dpp(0, __float_as_int(z), 0x12f, 0xf, 0xf, false));
;                         }
;                         cv[bj] = kc[bj][0] * pv + kc[bj][1] * cur + kc[bj][2] * nv + bc[bj];
	v_pk_mul_f32 v[94:95], v[94:95], v[138:139] op_sel_hi:[1,0]
	v_pk_mul_f32 v[96:97], v[96:97], v[138:139] op_sel_hi:[1,0]
	v_pk_mul_f32 v[30:31], v[30:31], v[138:139] op_sel_hi:[1,0]
	v_pk_mul_f32 v[32:33], v[32:33], v[138:139] op_sel_hi:[1,0]
	v_pk_mul_f32 v[86:87], v[86:87], v[138:139] op_sel_hi:[1,0]
	v_pk_mul_f32 v[88:89], v[88:89], v[138:139] op_sel_hi:[1,0]
	v_pk_mul_f32 v[22:23], v[22:23], v[138:139] op_sel_hi:[1,0]
	v_pk_mul_f32 v[24:25], v[24:25], v[138:139] op_sel_hi:[1,0]
	v_pk_mul_f32 v[90:91], v[90:91], v[140:141] op_sel_hi:[1,0]
	v_pk_mul_f32 v[92:93], v[92:93], v[140:141] op_sel_hi:[1,0]
	v_pk_mul_f32 v[26:27], v[26:27], v[140:141] op_sel_hi:[1,0]
	v_pk_mul_f32 v[28:29], v[28:29], v[140:141] op_sel_hi:[1,0]
	v_pk_mul_f32 v[82:83], v[82:83], v[140:141] op_sel_hi:[1,0]
	v_pk_mul_f32 v[84:85], v[84:85], v[140:141] op_sel_hi:[1,0]
	v_pk_mul_f32 v[18:19], v[18:19], v[140:141] op_sel_hi:[1,0]
	v_pk_mul_f32 v[20:21], v[20:21], v[140:141] op_sel_hi:[1,0]
	v_pk_mul_f32 v[78:79], v[78:79], v[142:143] op_sel_hi:[1,0]
	v_pk_mul_f32 v[80:81], v[80:81], v[142:143] op_sel_hi:[1,0]
	v_pk_mul_f32 v[14:15], v[14:15], v[142:143] op_sel_hi:[1,0]
	v_pk_mul_f32 v[16:17], v[16:17], v[142:143] op_sel_hi:[1,0]
	v_pk_mul_f32 v[70:71], v[70:71], v[142:143] op_sel_hi:[1,0]
	v_pk_mul_f32 v[72:73], v[72:73], v[142:143] op_sel_hi:[1,0]
	v_pk_mul_f32 v[6:7], v[6:7], v[142:143] op_sel_hi:[1,0]
	v_pk_mul_f32 v[8:9], v[8:9], v[142:143] op_sel_hi:[1,0]
	v_pk_mul_f32 v[74:75], v[74:75], v[144:145] op_sel_hi:[1,0]
	v_pk_mul_f32 v[76:77], v[76:77], v[144:145] op_sel_hi:[1,0]
	v_pk_mul_f32 v[10:11], v[10:11], v[144:145] op_sel_hi:[1,0]
	v_pk_mul_f32 v[12:13], v[12:13], v[144:145] op_sel_hi:[1,0]
	v_pk_mul_f32 v[66:67], v[66:67], v[144:145] op_sel_hi:[1,0]
	v_pk_mul_f32 v[68:69], v[68:69], v[144:145] op_sel_hi:[1,0]
	v_pk_mul_f32 v[2:3], v[2:3], v[144:145] op_sel_hi:[1,0]
	v_pk_mul_f32 v[4:5], v[4:5], v[144:145] op_sel_hi:[1,0]
	v_and_b32_e32 v131, 64, v241
	v_xor_b32_e32 v130, 16, v241
	v_add_u32_e32 v131, 64, v131
	v_lshl_add_u32 v176, s12, 8, v247
	v_cmp_lt_i32_e32 vcc, v130, v131
	v_xor_b32_e32 v132, 32, v241
	v_ashrrev_i32_e32 v177, 31, v176
	v_cndmask_b32_e32 v130, v241, v130, vcc
	v_cmp_lt_i32_e32 vcc, v132, v131
	v_lshlrev_b32_e32 v130, 2, v130
	v_or_b32_e32 v194, 16, v176
	v_cndmask_b32_e32 v131, v241, v132, vcc
	v_lshlrev_b64 v[132:133], 7, v[176:177]
	v_lshl_add_u64 v[136:137], v[152:153], 0, v[132:133]
	s_nop 0
	v_lshlrev_b32_e32 v131, 2, v131
	v_ashrrev_i32_e32 v195, 31, v194
	v_or_b32_e32 v192, 32, v176
	v_ashrrev_i32_e32 v193, 31, v192
	v_or_b32_e32 v160, 48, v176
	v_ashrrev_i32_e32 v161, 31, v160
	v_add_u32_e32 v158, 0x80, v176
	v_ashrrev_i32_e32 v159, 31, v158
	v_add_u32_e32 v186, 0x90, v176
	v_ashrrev_i32_e32 v187, 31, v186
	v_add_u32_e32 v184, 0xa0, v176
	v_ashrrev_i32_e32 v185, 31, v184
	v_add_u32_e32 v174, 0xb0, v176
	v_ashrrev_i32_e32 v175, 31, v174
	v_lshl_or_b32 v178, s16, 7, v250
	v_ashrrev_i32_e32 v179, 31, v178
	s_mov_b32 s13, 0xa000
	s_nop 0
	s_nop 0
	s_waitcnt lgkmcnt(0)
	s_waitcnt lgkmcnt(0)
	v_mov_b32_e32 v180, 1.0
	s_nop 0
	v_pk_mul_f32 v[208:209], v[122:123], v[180:181] op_sel_hi:[1,0]
	v_lshlrev_b64 v[122:123], 7, v[194:195]
	v_pk_mul_f32 v[220:221], v[126:127], v[180:181] op_sel_hi:[1,0]
	v_lshl_add_u64 v[126:127], v[152:153], 0, v[122:123]
	v_pk_mul_f32 v[212:213], v[128:129], v[180:181] op_sel_hi:[1,0]
	v_pk_mul_f32 v[198:199], v[124:125], v[180:181] op_sel_hi:[1,0]
	s_nop 0
	v_mov_b32_dpp v228, v220 row_ror:1 row_mask:0xf bank_mask:0xf
	v_mov_b32_dpp v229, v221 row_ror:1 row_mask:0xf bank_mask:0xf
	v_mov_b32_dpp v230, v212 row_ror:1 row_mask:0xf bank_mask:0xf
	v_mov_b32_dpp v231, v213 row_ror:1 row_mask:0xf bank_mask:0xf
	v_mov_b32_dpp v234, v208 row_ror:1 row_mask:0xf bank_mask:0xf
	v_mov_b32_dpp v235, v209 row_ror:1 row_mask:0xf bank_mask:0xf
	v_mov_b32_dpp v238, v198 row_ror:1 row_mask:0xf bank_mask:0xf
	v_mov_b32_dpp v239, v199 row_ror:1 row_mask:0xf bank_mask:0xf
	s_nop 0
	s_nop 0
	s_waitcnt lgkmcnt(0)
	s_waitcnt lgkmcnt(0)
	v_mov_b32_e32 v182, 1.0
	s_nop 0
	v_pk_mul_f32 v[190:191], v[114:115], v[182:183] op_sel_hi:[1,0]
	v_lshlrev_b64 v[114:115], 7, v[192:193]
	v_pk_mul_f32 v[200:201], v[118:119], v[182:183] op_sel_hi:[1,0]
	v_lshl_add_u64 v[118:119], v[152:153], 0, v[114:115]
	v_pk_mul_f32 v[196:197], v[120:121], v[182:183] op_sel_hi:[1,0]
	v_pk_mul_f32 v[188:189], v[116:117], v[182:183] op_sel_hi:[1,0]
	s_nop 0
	v_cndmask_b32_e64 v224, v220, v200, s[42:43]
	v_cndmask_b32_e64 v225, v212, v196, s[42:43]
	v_cndmask_b32_e64 v232, v213, v197, s[42:43]
	v_mov_b32_dpp v226, v224 row_ror:15 row_mask:0xf bank_mask:0xf
	v_cndmask_b32_e64 v224, v221, v201, s[42:43]
	v_cndmask_b32_e64 v233, v208, v190, s[42:43]
	v_cndmask_b32_e64 v236, v209, v191, s[42:43]
	v_mov_b32_dpp v227, v224 row_ror:15 row_mask:0xf bank_mask:0xf
	v_cndmask_b32_e64 v237, v198, v188, s[42:43]
	v_cndmask_b32_e64 v242, v199, v189, s[42:43]
	v_mov_b32_dpp v224, v225 row_ror:15 row_mask:0xf bank_mask:0xf
	v_mov_b32_dpp v225, v232 row_ror:15 row_mask:0xf bank_mask:0xf
	v_mov_b32_dpp v232, v233 row_ror:15 row_mask:0xf bank_mask:0xf
	s_waitcnt lgkmcnt(0)
; __device__ __forceinline__ unsigned cvt_pk_bf16(float lo, float hi) { unsigned r; asm volatile("v_cvt_pk_bf16_f32 %0, %1, %2" : "=v"(r) : "v"(lo), "v"(hi)); return r; }
; __device__ __forceinline__ float sigmoid_f(float x) { return fast_rcp(1.0f + fast_exp2(-1.4426950409f * x)); }
;     __device__ __forceinline__ void operator()(f32x4 (&acc)[2][2][4][2], const Unit& u, int wr, int wc, int fr, int fq) const {
;     ...
;         for (int n = 0; n < 2; ++n) {
;             const int j4 = u.pn * 128 + wc * 32 + 8 * fq + 4 * n;
;             f32x4 kc[2][3], bc[2];
; #pragma unroll
;             for (int bj = 0; bj < 2; ++bj) { bc[bj] = *(const f32x4*)(cb + bj * FF + j4);
; #pragma unroll
;                 for (int w = 0; w < 3; ++w) kc[bj][w] = *(const f32x4*)(ck + w * NUP + bj * FF + j4); }
; #pragma unroll
;             for (int ai = 0; ai < 2; ++ai) {
;                 const int grp = u.pm * 4 + ai * 2 + wr;
; #pragma unroll
;                 for (int m = 0; m < 4; ++m) {
;                     f32x4 cv[2];
; #pragma unroll
;                     for (int bj = 0; bj < 2; ++bj) {
;                         const f32x4 cur = acc[ai][bj][m][n], lo = acc[ai][bj][m > 0 ? m - 1 : 0][n], hi = acc[ai][bj][m < 3 ? m + 1 : 3][n];
;                         f32x4 pv, nv;
; #pragma unroll
;                         for (int idx = 0; idx < 4; ++idx) {
;                             const float y = (fr == 15) ? lo[idx] : cur[idx], z = (fr == 0) ? hi[idx] : cur[idx];
;                             pv[idx] = __int_as_float(__builtin_amdgcn_update_dpp(0, __float_as_int(y), 0x121, 0xf, 0xf, false));
;                             nv[idx] = __int_as_float(__builtin_amdgcn_update_dpp(0, __float_as_int(z), 0x12f, 0xf, 0xf, false));
;                         }
;                         cv[bj] = kc[bj][0] * pv + kc[bj][1] * cur + kc[bj][2] * nv + bc[bj];
;                     }
;                     const int row = row0 + ai * HALF + m * 16;
;                     const bool edge = (m == 0 && fr == 0) || (m == 3 && fr == 15);
;                     if (!edge) { const f32x4 gt = cv[0], vl = cv[1];
;                         u32x2 w; w.x = cvt_pk_bf16(gt[0] * sigmoid_f(gt[0]) * vl[0], gt[1] * sigmoid_f(gt[1]) * vl[1]); w.y = cvt_pk_bf16(gt[2] * sigmoid_f(gt[2]) * vl[2], gt[3] * sigmoid_f(gt[3]) * vl[3]);
;                         *(u32x2*)(ACT + (size_t)row * FF + j4) = w; }
	v_lshlrev_b64 v[114:115], 7, v[160:161]
	v_lshl_add_u64 v[118:119], v[152:153], 0, v[114:115]
	s_nop 0
	v_mov_b32_dpp v233, v236 row_ror:15 row_mask:0xf bank_mask:0xf
	v_mov_b32_dpp v236, v237 row_ror:15 row_mask:0xf bank_mask:0xf
	v_mov_b32_dpp v237, v242 row_ror:15 row_mask:0xf bank_mask:0xf
	s_waitcnt lgkmcnt(0)
	v_lshlrev_b64 v[114:115], 7, v[158:159]
	v_lshl_add_u64 v[118:119], v[152:153], 0, v[114:115]
	s_nop 0
	s_nop 0
	s_nop 0
	s_waitcnt lgkmcnt(0)
	v_lshlrev_b64 v[114:115], 7, v[186:187]
	v_lshl_add_u64 v[118:119], v[152:153], 0, v[114:115]
	s_nop 0
	s_nop 0
	s_nop 0
	s_waitcnt lgkmcnt(0)
	v_lshlrev_b64 v[114:115], 7, v[184:185]
	v_lshl_add_u64 v[118:119], v[152:153], 0, v[114:115]
	s_nop 0
	s_nop 0
	s_nop 0
	s_waitcnt lgkmcnt(0)
	v_lshlrev_b64 v[114:115], 7, v[174:175]
	v_lshl_add_u64 v[118:119], v[152:153], 0, v[114:115]
	s_nop 0
	s_nop 0
	s_nop 0
	s_waitcnt lgkmcnt(0)
	v_lshlrev_b64 v[114:115], 2, v[178:179]
	v_lshl_add_u64 v[204:205], s[18:19], 0, v[114:115]
	v_add_co_u32_e32 v206, vcc, s13, v204
	s_mov_b32 s13, 0x15000
	s_nop 0
	v_addc_co_u32_e32 v207, vcc, 0, v205, vcc
	v_add_co_u32_e32 v210, vcc, s13, v204
	v_lshl_add_u64 v[202:203], s[20:21], 0, v[114:115]
	s_nop 0
	v_addc_co_u32_e32 v211, vcc, 0, v205, vcc
	v_add_co_u32_e32 v214, vcc, s33, v202
	s_mov_b32 s13, 0x1a000
	s_nop 0
	v_addc_co_u32_e32 v215, vcc, 0, v203, vcc
	v_add_co_u32_e32 v216, vcc, s33, v204
	s_nop 1
	v_addc_co_u32_e32 v217, vcc, 0, v205, vcc
	v_add_co_u32_e32 v218, vcc, s65, v204
	global_load_dwordx4 v[114:117], v[202:203], off
	global_load_dwordx4 v[122:125], v[204:205], off
	v_addc_co_u32_e32 v219, vcc, 0, v205, vcc
	v_add_co_u32_e32 v222, vcc, s13, v204
	global_load_dwordx4 v[126:129], v[206:207], off offset:3072
	global_load_dwordx4 v[118:121], v[210:211], off offset:2048
	v_addc_co_u32_e32 v223, vcc, 0, v205, vcc
	global_load_dwordx4 v[130:133], v[214:215], off offset:1536
	global_load_dwordx4 v[134:137], v[216:217], off offset:1536
	global_load_dwordx4 v[138:141], v[218:219], off offset:512
	global_load_dwordx4 v[142:145], v[222:223], off offset:3584
	s_and_saveexec_b64 s[16:17], s[44:45]
	s_cbranch_execz .LBB0_757
	s_waitcnt vmcnt(6)
	v_pk_mul_f32 v[228:229], v[122:123], v[228:229]
	v_pk_mul_f32 v[230:231], v[124:125], v[230:231]
	s_waitcnt vmcnt(5)
	v_pk_fma_f32 v[228:229], v[220:221], v[126:127], v[228:229]
	v_pk_fma_f32 v[230:231], v[212:213], v[128:129], v[230:231]
	s_waitcnt vmcnt(4)
	v_pk_fma_f32 v[226:227], v[118:119], v[226:227], v[228:229]
	v_pk_fma_f32 v[224:225], v[120:121], v[224:225], v[230:231]
	v_pk_add_f32 v[226:227], v[114:115], v[226:227]
	v_pk_add_f32 v[224:225], v[116:117], v[224:225]
	v_mul_f32_e32 v228, 0xbfb8aa3b, v226
	v_mul_f32_e32 v229, 0xbfb8aa3b, v227
	v_exp_f32_e32 v228, v228
	v_exp_f32_e32 v229, v229
	s_waitcnt vmcnt(2)
	v_pk_mul_f32 v[238:239], v[136:137], v[238:239]
	v_pk_mul_f32 v[234:235], v[134:135], v[234:235]
	v_add_f32_e32 v228, 1.0, v228
	v_add_f32_e32 v229, 1.0, v229
	v_rcp_f32_e32 v228, v228
	v_rcp_f32_e32 v229, v229
	s_waitcnt vmcnt(1)
	v_pk_fma_f32 v[238:239], v[198:199], v[140:141], v[238:239]
	v_pk_fma_f32 v[234:235], v[208:209], v[138:139], v[234:235]
	v_mul_f32_e32 v226, v226, v228
	v_mul_f32_e32 v227, v227, v229
	v_mul_f32_e32 v228, 0xbfb8aa3b, v224
	v_mul_f32_e32 v229, 0xbfb8aa3b, v225
	v_exp_f32_e32 v228, v228
	v_exp_f32_e32 v229, v229
	s_waitcnt vmcnt(0)
	v_pk_fma_f32 v[236:237], v[144:145], v[236:237], v[238:239]
	v_pk_fma_f32 v[232:233], v[142:143], v[232:233], v[234:235]
	v_add_f32_e32 v228, 1.0, v228
	v_add_f32_e32 v229, 1.0, v229
	v_rcp_f32_e32 v228, v228
	v_rcp_f32_e32 v229, v229
	v_pk_add_f32 v[232:233], v[130:131], v[232:233]
	v_pk_add_f32 v[234:235], v[132:133], v[236:237]
	v_mul_f32_e32 v224, v224, v228
	v_mul_f32_e32 v225, v225, v229
	v_mul_f32_e32 v226, v226, v232
	v_mul_f32_e32 v227, v227, v233
	v_mul_f32_e32 v224, v224, v234
	v_mul_f32_e32 v225, v225, v235
	v_cvt_pk_bf16_f32 v226, v226, v227
	v_cvt_pk_bf16_f32 v227, v224, v225
	v_mov_b64_e32 v[224:225], s[30:31]
	v_mad_i64_i32 v[224:225], s[34:35], v176, s7, v[224:225]
	v_lshl_add_u64 v[224:225], v[178:179], 1, v[224:225]
	global_store_dwordx2 v[224:225], v[226:227], off

; __device__ __forceinline__ unsigned cvt_pk_bf16(float lo, float hi) { unsigned r; asm volatile("v_cvt_pk_bf16_f32 %0, %1, %2" : "=v"(r) : "v"(lo), "v"(hi)); return r; }
; __device__ __forceinline__ float sigmoid_f(float x) { return fast_rcp(1.0f + fast_exp2(-1.4426950409f * x)); }
;     __device__ __forceinline__ void operator()(f32x4 (&acc)[2][2][4][2], const Unit& u, int wr, int wc, int fr, int fq) const {
;     ...
;                     f32x4 cv[2];
; #pragma unroll
;                     for (int bj = 0; bj < 2; ++bj) {
;                         const f32x4 cur = acc[ai][bj][m][n], lo = acc[ai][bj][m > 0 ? m - 1 : 0][n], hi = acc[ai][bj][m < 3 ? m + 1 : 3][n];
;                         f32x4 pv, nv;
; #pragma unroll
;                         for (int idx = 0; idx < 4; ++idx) {
;                             const float y = (fr == 15) ? lo[idx] : cur[idx], z = (fr == 0) ? hi[idx] : cur[idx];
;                             pv[idx] = __int_as_float(__builtin_amdgcn_update_dpp(0, __float_as_int(y), 0x121, 0xf, 0xf, false));
;                             nv[idx] = __int_as_float(__builtin_amdgcn_update_dpp(0, __float_as_int(z), 0x12f, 0xf, 0xf, false));
;                         }
;                         cv[bj] = kc[bj][0] * pv + kc[bj][1] * cur + kc[bj][2] * nv + bc[bj];
;                     }
;                     const int row = row0 + ai * HALF + m * 16;
;                     const bool edge = (m == 0 && fr == 0) || (m == 3 && fr == 15);
;                     if (!edge) { const f32x4 gt = cv[0], vl = cv[1];
;                         u32x2 w; w.x = cvt_pk_bf16(gt[0] * sigmoid_f(gt[0]) * vl[0], gt[1] * sigmoid_f(gt[1]) * vl[1]); w.y = cvt_pk_bf16(gt[2] * sigmoid_f(gt[2]) * vl[2], gt[3] * sigmoid_f(gt[3]) * vl[3]);
;                         *(u32x2*)(ACT + (size_t)row * FF + j4) = w; }
.LBB0_759:
	s_or_b64 exec, exec, s[12:13]
	v_mov_b32_e32 v228, 1.0
	v_mov_b32_e32 v230, 1.0
	v_pk_mul_f32 v[238:239], v[110:111], v[228:229] op_sel_hi:[1,0]
	v_pk_mul_f32 v[234:235], v[102:103], v[228:229] op_sel_hi:[1,0]
	v_pk_mul_f32 v[236:237], v[112:113], v[228:229] op_sel_hi:[1,0]
	v_pk_mul_f32 v[110:111], v[108:109], v[230:231] op_sel_hi:[1,0]
	v_pk_mul_f32 v[102:103], v[100:101], v[230:231] op_sel_hi:[1,0]
	v_pk_mul_f32 v[108:109], v[98:99], v[230:231] op_sel_hi:[1,0]
	v_cndmask_b32_e64 v99, v200, v220, s[38:39]
	v_cndmask_b32_e64 v101, v200, v238, s[42:43]
	v_pk_mul_f32 v[232:233], v[104:105], v[228:229] op_sel_hi:[1,0]
	v_mov_b32_dpp v98, v99 row_ror:1 row_mask:0xf bank_mask:0xf
	v_mov_b32_dpp v100, v101 row_ror:15 row_mask:0xf bank_mask:0xf
	v_cndmask_b32_e64 v101, v201, v221, s[38:39]
	v_cndmask_b32_e64 v104, v201, v239, s[42:43]
	v_pk_mul_f32 v[112:113], v[106:107], v[230:231] op_sel_hi:[1,0]
	v_mov_b32_dpp v99, v101 row_ror:1 row_mask:0xf bank_mask:0xf
	v_cndmask_b32_e64 v105, v196, v212, s[38:39]
	v_cndmask_b32_e64 v107, v196, v236, s[42:43]
	v_mov_b32_dpp v101, v104 row_ror:15 row_mask:0xf bank_mask:0xf
	v_cndmask_b32_e64 v193, v197, v237, s[42:43]
	v_mov_b32_dpp v104, v105 row_ror:1 row_mask:0xf bank_mask:0xf
	v_mov_b32_dpp v106, v107 row_ror:15 row_mask:0xf bank_mask:0xf
	v_cndmask_b32_e64 v107, v197, v213, s[38:39]
	s_waitcnt vmcnt(6)
	v_pk_mul_f32 v[98:99], v[122:123], v[98:99]
	v_cndmask_b32_e64 v195, v190, v234, s[42:43]
	v_mov_b32_dpp v105, v107 row_ror:1 row_mask:0xf bank_mask:0xf
	s_waitcnt vmcnt(5)
	v_pk_fma_f32 v[98:99], v[200:201], v[126:127], v[98:99]
	v_mov_b32_dpp v107, v193 row_ror:15 row_mask:0xf bank_mask:0xf
	v_cndmask_b32_e64 v193, v190, v208, s[38:39]
	s_waitcnt vmcnt(4)
	v_pk_fma_f32 v[98:99], v[118:119], v[100:101], v[98:99]
	v_mov_b32_dpp v212, v195 row_ror:15 row_mask:0xf bank_mask:0xf
	v_mov_b32_dpp v208, v193 row_ror:1 row_mask:0xf bank_mask:0xf
	v_cndmask_b32_e64 v193, v191, v209, s[38:39]
	v_cndmask_b32_e64 v195, v191, v235, s[42:43]
	s_nop 0
	v_mov_b32_dpp v209, v193 row_ror:1 row_mask:0xf bank_mask:0xf
	v_cndmask_b32_e64 v193, v188, v198, s[38:39]
	v_pk_add_f32 v[98:99], v[114:115], v[98:99]
	v_mov_b32_dpp v213, v195 row_ror:15 row_mask:0xf bank_mask:0xf
	v_cndmask_b32_e64 v195, v188, v232, s[42:43]
	v_mov_b32_dpp v198, v193 row_ror:1 row_mask:0xf bank_mask:0xf
	v_cndmask_b32_e64 v193, v189, v199, s[38:39]
	v_mul_f32_e32 v100, 0xbfb8aa3b, v98
	v_mov_b32_dpp v220, v195 row_ror:15 row_mask:0xf bank_mask:0xf
	v_cndmask_b32_e64 v195, v189, v233, s[42:43]
	v_mov_b32_dpp v199, v193 row_ror:1 row_mask:0xf bank_mask:0xf
	v_exp_f32_e32 v193, v100
	v_mul_f32_e32 v100, 0xbfb8aa3b, v99
	v_mov_b32_dpp v221, v195 row_ror:15 row_mask:0xf bank_mask:0xf
	v_exp_f32_e32 v195, v100
	v_pk_mul_f32 v[104:105], v[124:125], v[104:105]
	s_waitcnt vmcnt(2)
	v_pk_mul_f32 v[208:209], v[134:135], v[208:209]
	v_pk_fma_f32 v[104:105], v[196:197], v[128:129], v[104:105]
	s_waitcnt vmcnt(1)
	v_pk_fma_f32 v[208:209], v[190:191], v[138:139], v[208:209]
	v_pk_fma_f32 v[100:101], v[120:121], v[106:107], v[104:105]
	v_add_f32_e32 v104, 1.0, v193
	v_add_f32_e32 v105, 1.0, v195
	v_rcp_f32_e32 v104, v104
	v_rcp_f32_e32 v105, v105
	v_pk_add_f32 v[100:101], v[116:117], v[100:101]
	v_pk_mul_f32 v[198:199], v[136:137], v[198:199]
	v_mul_f32_e32 v98, v98, v104
	v_mul_f32_e32 v99, v99, v105
	v_mul_f32_e32 v104, 0xbfb8aa3b, v100
	v_mul_f32_e32 v105, 0xbfb8aa3b, v101
	v_exp_f32_e32 v104, v104
	v_exp_f32_e32 v105, v105
	s_waitcnt vmcnt(0)
	v_pk_fma_f32 v[208:209], v[142:143], v[212:213], v[208:209]
	v_pk_fma_f32 v[198:199], v[188:189], v[140:141], v[198:199]
	v_add_f32_e32 v104, 1.0, v104
	v_add_f32_e32 v105, 1.0, v105
	v_rcp_f32_e32 v104, v104
	v_rcp_f32_e32 v105, v105
	v_pk_add_f32 v[208:209], v[130:131], v[208:209]
	v_pk_fma_f32 v[198:199], v[144:145], v[220:221], v[198:199]
	v_mul_f32_e32 v98, v98, v208
	v_mul_f32_e32 v99, v99, v209
	v_pk_add_f32 v[198:199], v[132:133], v[198:199]
	v_cvt_pk_bf16_f32 v98, v98, v99
	v_mul_f32_e32 v99, v100, v104
	v_mul_f32_e32 v100, v101, v105
	v_mul_f32_e32 v99, v99, v198
	v_mul_f32_e32 v100, v100, v199
	v_cvt_pk_bf16_f32 v99, v99, v100
	v_mov_b64_e32 v[100:101], s[30:31]
	v_mad_i64_i32 v[104:105], s[12:13], v194, s7, v[100:101]
	v_lshlrev_b64 v[194:195], 1, v[178:179]
	v_lshl_add_u64 v[104:105], v[104:105], 0, v[194:195]
	global_store_dwordx2 v[104:105], v[98:99], off
	v_cndmask_b32_e64 v99, v238, v200, s[38:39]
	v_cndmask_b32_e64 v107, v238, v112, s[42:43]
	v_cndmask_b32_e64 v193, v239, v113, s[42:43]
	v_mov_b32_dpp v98, v99 row_ror:1 row_mask:0xf bank_mask:0xf
	v_mov_b32_dpp v106, v107 row_ror:15 row_mask:0xf bank_mask:0xf
	v_cndmask_b32_e64 v107, v239, v201, s[38:39]
	v_cndmask_b32_e64 v199, v236, v110, s[42:43]
	s_nop 0
	v_mov_b32_dpp v99, v107 row_ror:1 row_mask:0xf bank_mask:0xf
	v_pk_mul_f32 v[98:99], v[122:123], v[98:99]
	v_mov_b32_dpp v198, v199 row_ror:15 row_mask:0xf bank_mask:0xf
	v_mov_b32_dpp v107, v193 row_ror:15 row_mask:0xf bank_mask:0xf
	v_cndmask_b32_e64 v193, v236, v196, s[38:39]
	v_pk_fma_f32 v[98:99], v[238:239], v[126:127], v[98:99]
	v_cndmask_b32_e64 v200, v237, v111, s[42:43]
	v_mov_b32_dpp v196, v193 row_ror:1 row_mask:0xf bank_mask:0xf
	v_cndmask_b32_e64 v193, v237, v197, s[38:39]
	v_pk_fma_f32 v[98:99], v[118:119], v[106:107], v[98:99]
	s_nop 0
	v_mov_b32_dpp v197, v193 row_ror:1 row_mask:0xf bank_mask:0xf
	v_cndmask_b32_e64 v193, v234, v190, s[38:39]
	v_pk_add_f32 v[98:99], v[114:115], v[98:99]
	v_mov_b32_dpp v199, v200 row_ror:15 row_mask:0xf bank_mask:0xf
	v_mov_b32_dpp v190, v193 row_ror:1 row_mask:0xf bank_mask:0xf
	v_cndmask_b32_e64 v193, v235, v191, s[38:39]
; __device__ __forceinline__ unsigned cvt_pk_bf16(float lo, float hi) { unsigned r; asm volatile("v_cvt_pk_bf16_f32 %0, %1, %2" : "=v"(r) : "v"(lo), "v"(hi)); return r; }
; __device__ __forceinline__ float sigmoid_f(float x) { return fast_rcp(1.0f + fast_exp2(-1.4426950409f * x)); }
;     __device__ __forceinline__ void operator()(f32x4 (&acc)[2][2][4][2], const Unit& u, int wr, int wc, int fr, int fq) const {
;     ...
;                     f32x4 cv[2];
; #pragma unroll
;                     for (int bj = 0; bj < 2; ++bj) {
;                         const f32x4 cur = acc[ai][bj][m][n], lo = acc[ai][bj][m > 0 ? m - 1 : 0][n], hi = acc[ai][bj][m < 3 ? m + 1 : 3][n];
;                         f32x4 pv, nv;
; #pragma unroll
;                         for (int idx = 0; idx < 4; ++idx) {
;                             const float y = (fr == 15) ? lo[idx] : cur[idx], z = (fr == 0) ? hi[idx] : cur[idx];
;                             pv[idx] = __int_as_float(__builtin_amdgcn_update_dpp(0, __float_as_int(y), 0x121, 0xf, 0xf, false));
;                             nv[idx] = __int_as_float(__builtin_amdgcn_update_dpp(0, __float_as_int(z), 0x12f, 0xf, 0xf, false));
;                         }
;                         cv[bj] = kc[bj][0] * pv + kc[bj][1] * cur + kc[bj][2] * nv + bc[bj];
;                     }
;                     const int row = row0 + ai * HALF + m * 16;
;                     const bool edge = (m == 0 && fr == 0) || (m == 3 && fr == 15);
;                     if (!edge) { const f32x4 gt = cv[0], vl = cv[1];
;                         u32x2 w; w.x = cvt_pk_bf16(gt[0] * sigmoid_f(gt[0]) * vl[0], gt[1] * sigmoid_f(gt[1]) * vl[1]); w.y = cvt_pk_bf16(gt[2] * sigmoid_f(gt[2]) * vl[2], gt[3] * sigmoid_f(gt[3]) * vl[3]);
;                         *(u32x2*)(ACT + (size_t)row * FF + j4) = w; }
	v_mul_f32_e32 v106, 0xbfb8aa3b, v98
	v_cndmask_b32_e64 v201, v234, v108, s[42:43]
	v_mov_b32_dpp v191, v193 row_ror:1 row_mask:0xf bank_mask:0xf
	v_cndmask_b32_e64 v193, v232, v188, s[38:39]
	v_cndmask_b32_e64 v208, v235, v109, s[42:43]
	s_nop 0
	v_mov_b32_dpp v188, v193 row_ror:1 row_mask:0xf bank_mask:0xf
	v_cndmask_b32_e64 v193, v233, v189, s[38:39]
	v_mov_b32_dpp v200, v201 row_ror:15 row_mask:0xf bank_mask:0xf
	s_nop 0
	v_mov_b32_dpp v189, v193 row_ror:1 row_mask:0xf bank_mask:0xf
	v_exp_f32_e32 v193, v106
	v_pk_mul_f32 v[190:191], v[134:135], v[190:191]
	v_mov_b32_dpp v201, v208 row_ror:15 row_mask:0xf bank_mask:0xf
	v_pk_fma_f32 v[190:191], v[234:235], v[138:139], v[190:191]
	v_mul_f32_e32 v106, 0xbfb8aa3b, v99
	v_add_f32_e32 v193, 1.0, v193
	v_pk_fma_f32 v[190:191], v[142:143], v[200:201], v[190:191]
	v_exp_f32_e32 v200, v106
	v_rcp_f32_e32 v193, v193
	v_pk_mul_f32 v[196:197], v[124:125], v[196:197]
	v_pk_add_f32 v[190:191], v[130:131], v[190:191]
	v_pk_fma_f32 v[196:197], v[236:237], v[128:129], v[196:197]
	v_mul_f32_e32 v98, v98, v193
	v_pk_fma_f32 v[106:107], v[120:121], v[198:199], v[196:197]
	v_add_f32_e32 v196, 1.0, v200
	v_pk_add_f32 v[106:107], v[116:117], v[106:107]
	v_rcp_f32_e32 v196, v196
	v_mul_f32_e32 v98, v98, v190
	v_mul_f32_e32 v190, 0xbfb8aa3b, v106
	v_mul_f32_e32 v193, 0xbfb8aa3b, v107
	v_exp_f32_e32 v190, v190
	v_exp_f32_e32 v193, v193
	v_mul_f32_e32 v99, v99, v196
	v_mul_f32_e32 v99, v99, v191
	v_add_f32_e32 v190, 1.0, v190
	v_add_f32_e32 v191, 1.0, v193
	v_cndmask_b32_e64 v209, v232, v102, s[42:43]
	v_rcp_f32_e32 v190, v190
	v_rcp_f32_e32 v191, v191
	v_mov_b32_dpp v208, v209 row_ror:15 row_mask:0xf bank_mask:0xf
	v_cndmask_b32_e64 v212, v233, v103, s[42:43]
	v_pk_mul_f32 v[188:189], v[136:137], v[188:189]
	v_cvt_pk_bf16_f32 v98, v98, v99
	v_mul_f32_e32 v99, v106, v190
	v_mov_b32_dpp v209, v212 row_ror:15 row_mask:0xf bank_mask:0xf
	v_pk_fma_f32 v[188:189], v[232:233], v[140:141], v[188:189]
	v_mul_f32_e32 v106, v107, v191
	v_pk_fma_f32 v[188:189], v[144:145], v[208:209], v[188:189]
	v_mad_i64_i32 v[100:101], s[12:13], v192, s7, v[100:101]
	v_pk_add_f32 v[188:189], v[132:133], v[188:189]
	v_mul_f32_e32 v99, v99, v188
	v_mul_f32_e32 v106, v106, v189
	v_cvt_pk_bf16_f32 v99, v99, v106
	v_lshl_add_u64 v[106:107], v[100:101], 0, v[194:195]
	global_store_dwordx2 v[106:107], v[98:99], off
	v_cndmask_b32_e64 v98, v112, v238, s[38:39]
	v_cndmask_b32_e64 v99, v111, v237, s[38:39]
	s_nop 0
	v_mov_b32_dpp v188, v98 row_ror:1 row_mask:0xf bank_mask:0xf
	v_cndmask_b32_e64 v98, v113, v239, s[38:39]
	v_cndmask_b32_e64 v192, v108, v234, s[38:39]
	s_nop 0
	v_mov_b32_dpp v189, v98 row_ror:1 row_mask:0xf bank_mask:0xf
	v_cndmask_b32_e64 v98, v110, v236, s[38:39]
	v_cndmask_b32_e64 v193, v109, v235, s[38:39]
	v_cndmask_b32_e64 v198, v102, v232, s[38:39]
	v_cndmask_b32_e64 v199, v103, v233, s[38:39]
	v_mov_b32_dpp v190, v98 row_ror:1 row_mask:0xf bank_mask:0xf
	v_mov_b32_dpp v191, v99 row_ror:1 row_mask:0xf bank_mask:0xf
	v_mov_b32_dpp v196, v192 row_ror:1 row_mask:0xf bank_mask:0xf
	v_mov_b32_dpp v197, v193 row_ror:1 row_mask:0xf bank_mask:0xf
	v_mov_b32_dpp v200, v198 row_ror:1 row_mask:0xf bank_mask:0xf
	v_mov_b32_dpp v201, v199 row_ror:1 row_mask:0xf bank_mask:0xf
	v_mov_b32_dpp v100, v112 row_ror:15 row_mask:0xf bank_mask:0xf
	v_mov_b32_dpp v101, v113 row_ror:15 row_mask:0xf bank_mask:0xf
	v_mov_b32_dpp v98, v110 row_ror:15 row_mask:0xf bank_mask:0xf
	v_mov_b32_dpp v99, v111 row_ror:15 row_mask:0xf bank_mask:0xf
	v_mov_b32_dpp v192, v108 row_ror:15 row_mask:0xf bank_mask:0xf
	v_mov_b32_dpp v193, v109 row_ror:15 row_mask:0xf bank_mask:0xf
	v_mov_b32_dpp v198, v102 row_ror:15 row_mask:0xf bank_mask:0xf
	v_mov_b32_dpp v199, v103 row_ror:15 row_mask:0xf bank_mask:0xf
	s_and_saveexec_b64 s[12:13], s[40:41]
	s_movk_i32 s94, 0x1000
	s_movk_i32 s95, 0x3000
	s_cbranch_execz .LBB0_761
	v_pk_mul_f32 v[188:189], v[122:123], v[188:189]
	v_pk_mul_f32 v[190:191], v[124:125], v[190:191]
	v_pk_fma_f32 v[188:189], v[112:113], v[126:127], v[188:189]
	v_pk_fma_f32 v[190:191], v[110:111], v[128:129], v[190:191]
	v_pk_fma_f32 v[100:101], v[118:119], v[100:101], v[188:189]
	v_pk_fma_f32 v[98:99], v[120:121], v[98:99], v[190:191]
	v_pk_add_f32 v[100:101], v[114:115], v[100:101]
	v_pk_add_f32 v[98:99], v[116:117], v[98:99]
	v_mul_f32_e32 v188, 0xbfb8aa3b, v100
	v_mul_f32_e32 v189, 0xbfb8aa3b, v101
	v_exp_f32_e32 v188, v188
	v_exp_f32_e32 v189, v189
	v_pk_mul_f32 v[200:201], v[136:137], v[200:201]
	v_pk_mul_f32 v[196:197], v[134:135], v[196:197]
	v_add_f32_e32 v188, 1.0, v188
	v_add_f32_e32 v189, 1.0, v189
	v_rcp_f32_e32 v188, v188
	v_rcp_f32_e32 v189, v189
	v_pk_fma_f32 v[200:201], v[102:103], v[140:141], v[200:201]
	v_pk_fma_f32 v[196:197], v[108:109], v[138:139], v[196:197]
	v_mul_f32_e32 v100, v100, v188
	v_mul_f32_e32 v101, v101, v189
	v_mul_f32_e32 v188, 0xbfb8aa3b, v98
	v_mul_f32_e32 v189, 0xbfb8aa3b, v99
	v_exp_f32_e32 v188, v188
	v_exp_f32_e32 v189, v189
	v_pk_fma_f32 v[198:199], v[144:145], v[198:199], v[200:201]
	v_pk_fma_f32 v[192:193], v[142:143], v[192:193], v[196:197]
	v_add_f32_e32 v188, 1.0, v188
	v_add_f32_e32 v189, 1.0, v189
	v_rcp_f32_e32 v188, v188
	v_rcp_f32_e32 v189, v189
	v_pk_add_f32 v[192:193], v[130:131], v[192:193]
	v_pk_add_f32 v[196:197], v[132:133], v[198:199]
	v_mul_f32_e32 v98, v98, v188
	v_mul_f32_e32 v99, v99, v189
	v_mul_f32_e32 v100, v100, v192
	v_mul_f32_e32 v101, v101, v193
	v_mul_f32_e32 v98, v98, v196
	v_mul_f32_e32 v99, v99, v197
	v_cvt_pk_bf16_f32 v100, v100, v101
	v_cvt_pk_bf16_f32 v101, v98, v99
	v_mov_b64_e32 v[98:99], s[30:31]
	v_mad_i64_i32 v[98:99], s[34:35], v160, s7, v[98:99]
	v_lshl_add_u64 v[98:99], v[178:179], 1, v[98:99]
	global_store_dwordx2 v[98:99], v[100:101], off

; __device__ __forceinline__ unsigned cvt_pk_bf16(float lo, float hi) { unsigned r; asm volatile("v_cvt_pk_bf16_f32 %0, %1, %2" : "=v"(r) : "v"(lo), "v"(hi)); return r; }
; __device__ __forceinline__ float sigmoid_f(float x) { return fast_rcp(1.0f + fast_exp2(-1.4426950409f * x)); }
;     __device__ __forceinline__ void operator()(f32x4 (&acc)[2][2][4][2], const Unit& u, int wr, int wc, int fr, int fq) const {
;     ...
;                     f32x4 cv[2];
; #pragma unroll
;                     for (int bj = 0; bj < 2; ++bj) {
;                         const f32x4 cur = acc[ai][bj][m][n], lo = acc[ai][bj][m > 0 ? m - 1 : 0][n], hi = acc[ai][bj][m < 3 ? m + 1 : 3][n];
;                         f32x4 pv, nv;
; #pragma unroll
;                         for (int idx = 0; idx < 4; ++idx) {
;                             const float y = (fr == 15) ? lo[idx] : cur[idx], z = (fr == 0) ? hi[idx] : cur[idx];
;                             pv[idx] = __int_as_float(__builtin_amdgcn_update_dpp(0, __float_as_int(y), 0x121, 0xf, 0xf, false));
;                             nv[idx] = __int_as_float(__builtin_amdgcn_update_dpp(0, __float_as_int(z), 0x12f, 0xf, 0xf, false));
;                         }
;                         cv[bj] = kc[bj][0] * pv + kc[bj][1] * cur + kc[bj][2] * nv + bc[bj];
;                     }
;                     const int row = row0 + ai * HALF + m * 16;
;                     const bool edge = (m == 0 && fr == 0) || (m == 3 && fr == 15);
;                     if (!edge) { const f32x4 gt = cv[0], vl = cv[1];
;                         u32x2 w; w.x = cvt_pk_bf16(gt[0] * sigmoid_f(gt[0]) * vl[0], gt[1] * sigmoid_f(gt[1]) * vl[1]); w.y = cvt_pk_bf16(gt[2] * sigmoid_f(gt[2]) * vl[2], gt[3] * sigmoid_f(gt[3]) * vl[3]);
;                         *(u32x2*)(ACT + (size_t)row * FF + j4) = w; }
.LBB0_763:
	s_or_b64 exec, exec, s[12:13]
	v_mov_b32_e32 v108, 1.0
	v_mov_b32_e32 v110, 1.0
	v_pk_mul_f32 v[196:197], v[94:95], v[108:109] op_sel_hi:[1,0]
	v_pk_mul_f32 v[94:95], v[88:89], v[108:109] op_sel_hi:[1,0]
	v_pk_mul_f32 v[192:193], v[96:97], v[108:109] op_sel_hi:[1,0]
	v_pk_mul_f32 v[88:89], v[90:91], v[110:111] op_sel_hi:[1,0]
	v_pk_mul_f32 v[96:97], v[86:87], v[108:109] op_sel_hi:[1,0]
	v_pk_mul_f32 v[86:87], v[92:93], v[110:111] op_sel_hi:[1,0]
	v_cndmask_b32_e64 v90, v196, v88, s[42:43]
	v_cndmask_b32_e64 v91, v192, v86, s[42:43]
	s_nop 0
	v_mov_b32_dpp v92, v90 row_ror:15 row_mask:0xf bank_mask:0xf
	v_cndmask_b32_e64 v90, v197, v89, s[42:43]
	v_pk_mul_f32 v[82:83], v[82:83], v[110:111] op_sel_hi:[1,0]
	v_cndmask_b32_e64 v109, v193, v87, s[42:43]
	v_mov_b32_dpp v93, v90 row_ror:15 row_mask:0xf bank_mask:0xf
	v_pk_mul_f32 v[84:85], v[84:85], v[110:111] op_sel_hi:[1,0]
	v_mov_b32_dpp v90, v91 row_ror:15 row_mask:0xf bank_mask:0xf
	v_mov_b32_dpp v91, v109 row_ror:15 row_mask:0xf bank_mask:0xf
	v_cndmask_b32_e64 v109, v96, v82, s[42:43]
	s_nop 1
	v_mov_b32_dpp v188, v109 row_ror:15 row_mask:0xf bank_mask:0xf
	v_cndmask_b32_e64 v109, v97, v83, s[42:43]
	s_nop 1
	v_mov_b32_dpp v189, v109 row_ror:15 row_mask:0xf bank_mask:0xf
	v_cndmask_b32_e64 v109, v94, v84, s[42:43]
	s_nop 1
	v_mov_b32_dpp v198, v109 row_ror:15 row_mask:0xf bank_mask:0xf
	v_cndmask_b32_e64 v109, v95, v85, s[42:43]
	v_mov_b32_dpp v102, v196 row_ror:1 row_mask:0xf bank_mask:0xf
	v_mov_b32_dpp v103, v197 row_ror:1 row_mask:0xf bank_mask:0xf
	v_mov_b32_dpp v112, v192 row_ror:1 row_mask:0xf bank_mask:0xf
	v_mov_b32_dpp v113, v193 row_ror:1 row_mask:0xf bank_mask:0xf
	v_mov_b32_dpp v190, v96 row_ror:1 row_mask:0xf bank_mask:0xf
	v_mov_b32_dpp v191, v97 row_ror:1 row_mask:0xf bank_mask:0xf
	v_mov_b32_dpp v200, v94 row_ror:1 row_mask:0xf bank_mask:0xf
	v_mov_b32_dpp v201, v95 row_ror:1 row_mask:0xf bank_mask:0xf
	v_mov_b32_dpp v199, v109 row_ror:15 row_mask:0xf bank_mask:0xf
	s_and_saveexec_b64 s[12:13], s[44:45]
	s_cbranch_execz .LBB0_765
	v_pk_mul_f32 v[102:103], v[122:123], v[102:103]
	v_pk_mul_f32 v[112:113], v[124:125], v[112:113]
	v_pk_fma_f32 v[102:103], v[196:197], v[126:127], v[102:103]
	v_pk_fma_f32 v[112:113], v[192:193], v[128:129], v[112:113]
	v_pk_fma_f32 v[92:93], v[118:119], v[92:93], v[102:103]
	v_pk_fma_f32 v[90:91], v[120:121], v[90:91], v[112:113]
	v_pk_add_f32 v[92:93], v[114:115], v[92:93]
	v_pk_add_f32 v[90:91], v[116:117], v[90:91]
	v_mul_f32_e32 v102, 0xbfb8aa3b, v92
	v_mul_f32_e32 v103, 0xbfb8aa3b, v93
	v_exp_f32_e32 v102, v102
	v_exp_f32_e32 v103, v103
	v_pk_mul_f32 v[200:201], v[136:137], v[200:201]
	v_pk_mul_f32 v[190:191], v[134:135], v[190:191]
	v_add_f32_e32 v102, 1.0, v102
	v_add_f32_e32 v103, 1.0, v103
	v_rcp_f32_e32 v102, v102
	v_rcp_f32_e32 v103, v103
	v_pk_fma_f32 v[200:201], v[94:95], v[140:141], v[200:201]
	v_pk_fma_f32 v[190:191], v[96:97], v[138:139], v[190:191]
	v_mul_f32_e32 v92, v92, v102
	v_mul_f32_e32 v93, v93, v103
	v_mul_f32_e32 v102, 0xbfb8aa3b, v90
	v_mul_f32_e32 v103, 0xbfb8aa3b, v91
	v_exp_f32_e32 v102, v102
	v_exp_f32_e32 v103, v103
	v_pk_fma_f32 v[198:199], v[144:145], v[198:199], v[200:201]
	v_pk_fma_f32 v[188:189], v[142:143], v[188:189], v[190:191]
	v_add_f32_e32 v102, 1.0, v102
	v_add_f32_e32 v103, 1.0, v103
	v_rcp_f32_e32 v102, v102
	v_rcp_f32_e32 v103, v103
	v_pk_add_f32 v[188:189], v[130:131], v[188:189]
	v_pk_add_f32 v[190:191], v[132:133], v[198:199]
	v_mul_f32_e32 v90, v90, v102
	v_mul_f32_e32 v91, v91, v103
	v_mul_f32_e32 v92, v92, v188
	v_mul_f32_e32 v93, v93, v189
	v_mul_f32_e32 v90, v90, v190
	v_mul_f32_e32 v91, v91, v191
	v_cvt_pk_bf16_f32 v92, v92, v93
	v_cvt_pk_bf16_f32 v93, v90, v91
	v_mov_b64_e32 v[90:91], s[30:31]
	v_mad_i64_i32 v[90:91], s[34:35], v158, s7, v[90:91]
	v_lshl_add_u64 v[90:91], v[178:179], 1, v[90:91]
	global_store_dwordx2 v[90:91], v[92:93], off

; __device__ __forceinline__ unsigned cvt_pk_bf16(float lo, float hi) { unsigned r; asm volatile("v_cvt_pk_bf16_f32 %0, %1, %2" : "=v"(r) : "v"(lo), "v"(hi)); return r; }
; __device__ __forceinline__ float sigmoid_f(float x) { return fast_rcp(1.0f + fast_exp2(-1.4426950409f * x)); }
;     __device__ __forceinline__ void operator()(f32x4 (&acc)[2][2][4][2], const Unit& u, int wr, int wc, int fr, int fq) const {
;     ...
;                     f32x4 cv[2];
; #pragma unroll
;                     for (int bj = 0; bj < 2; ++bj) {
;                         const f32x4 cur = acc[ai][bj][m][n], lo = acc[ai][bj][m > 0 ? m - 1 : 0][n], hi = acc[ai][bj][m < 3 ? m + 1 : 3][n];
;                         f32x4 pv, nv;
; #pragma unroll
;                         for (int idx = 0; idx < 4; ++idx) {
;                             const float y = (fr == 15) ? lo[idx] : cur[idx], z = (fr == 0) ? hi[idx] : cur[idx];
;                             pv[idx] = __int_as_float(__builtin_amdgcn_update_dpp(0, __float_as_int(y), 0x121, 0xf, 0xf, false));
;                             nv[idx] = __int_as_float(__builtin_amdgcn_update_dpp(0, __float_as_int(z), 0x12f, 0xf, 0xf, false));
;                         }
;                         cv[bj] = kc[bj][0] * pv + kc[bj][1] * cur + kc[bj][2] * nv + bc[bj];
;                     }
;                     const int row = row0 + ai * HALF + m * 16;
;                     const bool edge = (m == 0 && fr == 0) || (m == 3 && fr == 15);
;                     if (!edge) { const f32x4 gt = cv[0], vl = cv[1];
;                         u32x2 w; w.x = cvt_pk_bf16(gt[0] * sigmoid_f(gt[0]) * vl[0], gt[1] * sigmoid_f(gt[1]) * vl[1]); w.y = cvt_pk_bf16(gt[2] * sigmoid_f(gt[2]) * vl[2], gt[3] * sigmoid_f(gt[3]) * vl[3]);
;                         *(u32x2*)(ACT + (size_t)row * FF + j4) = w; }
.LBB0_767:
	s_or_b64 exec, exec, s[12:13]
	v_mov_b32_e32 v188, 1.0
	s_waitcnt lgkmcnt(0)
	v_mov_b32_e32 v190, 1.0
	v_pk_mul_f32 v[92:93], v[78:79], v[188:189] op_sel_hi:[1,0]
	v_pk_mul_f32 v[90:91], v[80:81], v[188:189] op_sel_hi:[1,0]
	v_pk_mul_f32 v[78:79], v[72:73], v[188:189] op_sel_hi:[1,0]
	v_pk_mul_f32 v[80:81], v[70:71], v[188:189] op_sel_hi:[1,0]
	v_pk_mul_f32 v[70:71], v[76:77], v[190:191] op_sel_hi:[1,0]
	v_pk_mul_f32 v[72:73], v[74:75], v[190:191] op_sel_hi:[1,0]
	v_cndmask_b32_e64 v75, v88, v196, s[38:39]
	v_cndmask_b32_e64 v77, v88, v92, s[42:43]
	v_cndmask_b32_e64 v109, v89, v93, s[42:43]
	v_mov_b32_dpp v74, v75 row_ror:1 row_mask:0xf bank_mask:0xf
	v_mov_b32_dpp v76, v77 row_ror:15 row_mask:0xf bank_mask:0xf
	v_cndmask_b32_e64 v77, v89, v197, s[38:39]
	v_cndmask_b32_e64 v111, v86, v90, s[42:43]
	s_nop 0
	v_mov_b32_dpp v75, v77 row_ror:1 row_mask:0xf bank_mask:0xf
	v_pk_mul_f32 v[74:75], v[122:123], v[74:75]
	v_mov_b32_dpp v196, v111 row_ror:15 row_mask:0xf bank_mask:0xf
	v_mov_b32_dpp v77, v109 row_ror:15 row_mask:0xf bank_mask:0xf
	v_cndmask_b32_e64 v109, v86, v192, s[38:39]
	v_pk_fma_f32 v[74:75], v[126:127], v[88:89], v[74:75]
	v_cndmask_b32_e64 v111, v87, v91, s[42:43]
	v_mov_b32_dpp v192, v109 row_ror:1 row_mask:0xf bank_mask:0xf
	v_cndmask_b32_e64 v109, v87, v193, s[38:39]
	v_pk_fma_f32 v[74:75], v[118:119], v[76:77], v[74:75]
	s_nop 0
	v_mov_b32_dpp v193, v109 row_ror:1 row_mask:0xf bank_mask:0xf
	v_cndmask_b32_e64 v109, v82, v96, s[38:39]
	v_pk_add_f32 v[74:75], v[114:115], v[74:75]
	v_mov_b32_dpp v197, v111 row_ror:15 row_mask:0xf bank_mask:0xf
	v_mov_b32_dpp v96, v109 row_ror:1 row_mask:0xf bank_mask:0xf
	v_cndmask_b32_e64 v109, v83, v97, s[38:39]
	v_mul_f32_e32 v76, 0xbfb8aa3b, v74
	v_cndmask_b32_e64 v111, v82, v80, s[42:43]
	v_mov_b32_dpp v97, v109 row_ror:1 row_mask:0xf bank_mask:0xf
	v_cndmask_b32_e64 v109, v84, v94, s[38:39]
	s_nop 1
	v_mov_b32_dpp v94, v109 row_ror:1 row_mask:0xf bank_mask:0xf
	v_cndmask_b32_e64 v109, v85, v95, s[38:39]
	v_mov_b32_dpp v198, v111 row_ror:15 row_mask:0xf bank_mask:0xf
	v_cndmask_b32_e64 v111, v83, v81, s[42:43]
	v_mov_b32_dpp v95, v109 row_ror:1 row_mask:0xf bank_mask:0xf
	v_exp_f32_e32 v109, v76
	v_mov_b32_dpp v199, v111 row_ror:15 row_mask:0xf bank_mask:0xf
	v_cndmask_b32_e64 v111, v84, v78, s[42:43]
	v_mul_f32_e32 v76, 0xbfb8aa3b, v75
	s_nop 0
	v_mov_b32_dpp v200, v111 row_ror:15 row_mask:0xf bank_mask:0xf
	v_cndmask_b32_e64 v111, v85, v79, s[42:43]
	v_add_f32_e32 v109, 1.0, v109
	v_rcp_f32_e32 v109, v109
	v_mov_b32_dpp v201, v111 row_ror:15 row_mask:0xf bank_mask:0xf
	v_exp_f32_e32 v111, v76
	v_pk_mul_f32 v[96:97], v[134:135], v[96:97]
	v_pk_mul_f32 v[192:193], v[124:125], v[192:193]
	v_pk_fma_f32 v[96:97], v[82:83], v[138:139], v[96:97]
	v_pk_fma_f32 v[192:193], v[128:129], v[86:87], v[192:193]
	v_pk_fma_f32 v[96:97], v[142:143], v[198:199], v[96:97]
	v_pk_fma_f32 v[76:77], v[120:121], v[196:197], v[192:193]
	v_pk_add_f32 v[96:97], v[130:131], v[96:97]
	v_add_f32_e32 v111, 1.0, v111
	v_pk_add_f32 v[76:77], v[116:117], v[76:77]
	v_mul_f32_e32 v74, v74, v109
	v_rcp_f32_e32 v111, v111
	v_mul_f32_e32 v74, v74, v96
	v_mul_f32_e32 v96, 0xbfb8aa3b, v76
	v_mul_f32_e32 v109, 0xbfb8aa3b, v77
	v_exp_f32_e32 v96, v96
	v_exp_f32_e32 v109, v109
	v_mul_f32_e32 v75, v75, v111
	v_mul_f32_e32 v75, v75, v97
	v_add_f32_e32 v96, 1.0, v96
	v_add_f32_e32 v97, 1.0, v109
	v_rcp_f32_e32 v96, v96
	v_rcp_f32_e32 v97, v97
	v_pk_mul_f32 v[94:95], v[136:137], v[94:95]
	v_cvt_pk_bf16_f32 v74, v74, v75
	v_mul_f32_e32 v75, v76, v96
	v_pk_fma_f32 v[94:95], v[84:85], v[140:141], v[94:95]
	v_mul_f32_e32 v76, v77, v97
	v_pk_fma_f32 v[94:95], v[144:145], v[200:201], v[94:95]
	v_cndmask_b32_e64 v89, v93, v89, s[38:39]
	v_pk_add_f32 v[94:95], v[132:133], v[94:95]
	v_cndmask_b32_e64 v96, v91, v71, s[42:43]
	v_mul_f32_e32 v75, v75, v94
	v_mul_f32_e32 v76, v76, v95
	v_cvt_pk_bf16_f32 v75, v75, v76
	v_mov_b64_e32 v[76:77], s[30:31]
	v_mad_i64_i32 v[94:95], s[12:13], v186, s7, v[76:77]
	v_lshl_add_u64 v[186:187], v[94:95], 0, v[194:195]
	global_store_dwordx2 v[186:187], v[74:75], off
	v_cndmask_b32_e64 v75, v92, v88, s[38:39]
	v_cndmask_b32_e64 v94, v92, v72, s[42:43]
	s_nop 0
	v_mov_b32_dpp v74, v75 row_ror:1 row_mask:0xf bank_mask:0xf
	s_nop 0
	v_mov_b32_dpp v88, v94 row_ror:15 row_mask:0xf bank_mask:0xf
	v_cndmask_b32_e64 v94, v93, v73, s[42:43]
	v_mov_b32_dpp v75, v89 row_ror:1 row_mask:0xf bank_mask:0xf
	v_pk_mul_f32 v[74:75], v[122:123], v[74:75]
	v_cndmask_b32_e64 v95, v90, v70, s[42:43]
	v_mov_b32_dpp v89, v94 row_ror:15 row_mask:0xf bank_mask:0xf
	v_pk_fma_f32 v[74:75], v[126:127], v[92:93], v[74:75]
	v_cndmask_b32_e64 v94, v90, v86, s[38:39]
	v_pk_fma_f32 v[74:75], v[118:119], v[88:89], v[74:75]
	v_pk_add_f32 v[74:75], v[114:115], v[74:75]
	v_pk_mul_f32 v[66:67], v[66:67], v[190:191] op_sel_hi:[1,0]
	v_mov_b32_dpp v86, v94 row_ror:1 row_mask:0xf bank_mask:0xf
	v_mul_f32_e32 v88, 0xbfb8aa3b, v74
	v_exp_f32_e32 v88, v88
	v_mov_b32_dpp v94, v95 row_ror:15 row_mask:0xf bank_mask:0xf
	v_cndmask_b32_e64 v95, v91, v87, s[38:39]
	v_cndmask_b32_e64 v97, v80, v66, s[42:43]
	v_mul_f32_e32 v89, 0xbfb8aa3b, v75
	v_mov_b32_dpp v87, v95 row_ror:1 row_mask:0xf bank_mask:0xf
	v_add_f32_e32 v88, 1.0, v88
	v_exp_f32_e32 v89, v89
	v_mov_b32_dpp v95, v96 row_ror:15 row_mask:0xf bank_mask:0xf
	v_cndmask_b32_e64 v96, v80, v82, s[38:39]
; __device__ __forceinline__ unsigned cvt_pk_bf16(float lo, float hi) { unsigned r; asm volatile("v_cvt_pk_bf16_f32 %0, %1, %2" : "=v"(r) : "v"(lo), "v"(hi)); return r; }
; __device__ __forceinline__ float sigmoid_f(float x) { return fast_rcp(1.0f + fast_exp2(-1.4426950409f * x)); }
;     __device__ __forceinline__ void operator()(f32x4 (&acc)[2][2][4][2], const Unit& u, int wr, int wc, int fr, int fq) const {
;     ...
;                     f32x4 cv[2];
; #pragma unroll
;                     for (int bj = 0; bj < 2; ++bj) {
;                         const f32x4 cur = acc[ai][bj][m][n], lo = acc[ai][bj][m > 0 ? m - 1 : 0][n], hi = acc[ai][bj][m < 3 ? m + 1 : 3][n];
;                         f32x4 pv, nv;
; #pragma unroll
;                         for (int idx = 0; idx < 4; ++idx) {
;                             const float y = (fr == 15) ? lo[idx] : cur[idx], z = (fr == 0) ? hi[idx] : cur[idx];
;                             pv[idx] = __int_as_float(__builtin_amdgcn_update_dpp(0, __float_as_int(y), 0x121, 0xf, 0xf, false));
;                             nv[idx] = __int_as_float(__builtin_amdgcn_update_dpp(0, __float_as_int(z), 0x12f, 0xf, 0xf, false));
;                         }
;                         cv[bj] = kc[bj][0] * pv + kc[bj][1] * cur + kc[bj][2] * nv + bc[bj];
;                     }
;                     const int row = row0 + ai * HALF + m * 16;
;                     const bool edge = (m == 0 && fr == 0) || (m == 3 && fr == 15);
;                     if (!edge) { const f32x4 gt = cv[0], vl = cv[1];
;                         u32x2 w; w.x = cvt_pk_bf16(gt[0] * sigmoid_f(gt[0]) * vl[0], gt[1] * sigmoid_f(gt[1]) * vl[1]); w.y = cvt_pk_bf16(gt[2] * sigmoid_f(gt[2]) * vl[2], gt[3] * sigmoid_f(gt[3]) * vl[3]);
;                         *(u32x2*)(ACT + (size_t)row * FF + j4) = w; }
	v_rcp_f32_e32 v88, v88
	v_cndmask_b32_e64 v109, v81, v67, s[42:43]
	v_mov_b32_dpp v82, v96 row_ror:1 row_mask:0xf bank_mask:0xf
	v_pk_mul_f32 v[86:87], v[124:125], v[86:87]
	v_add_f32_e32 v89, 1.0, v89
	v_mov_b32_dpp v96, v97 row_ror:15 row_mask:0xf bank_mask:0xf
	v_cndmask_b32_e64 v97, v81, v83, s[38:39]
	v_pk_fma_f32 v[86:87], v[128:129], v[90:91], v[86:87]
	v_mul_f32_e32 v74, v74, v88
	v_mov_b32_dpp v83, v97 row_ror:1 row_mask:0xf bank_mask:0xf
	v_pk_mul_f32 v[82:83], v[134:135], v[82:83]
	v_pk_fma_f32 v[86:87], v[120:121], v[94:95], v[86:87]
	v_mov_b32_dpp v97, v109 row_ror:15 row_mask:0xf bank_mask:0xf
	v_pk_fma_f32 v[82:83], v[138:139], v[80:81], v[82:83]
	v_pk_add_f32 v[86:87], v[116:117], v[86:87]
	v_pk_fma_f32 v[82:83], v[142:143], v[96:97], v[82:83]
	v_rcp_f32_e32 v89, v89
	v_pk_add_f32 v[82:83], v[130:131], v[82:83]
	v_mul_f32_e32 v88, 0xbfb8aa3b, v87
	v_mul_f32_e32 v74, v74, v82
	v_mul_f32_e32 v82, 0xbfb8aa3b, v86
	v_exp_f32_e32 v82, v82
	v_exp_f32_e32 v88, v88
	v_cndmask_b32_e64 v109, v78, v84, s[38:39]
	v_mul_f32_e32 v75, v75, v89
	v_pk_mul_f32 v[68:69], v[68:69], v[190:191] op_sel_hi:[1,0]
	v_mov_b32_dpp v84, v109 row_ror:1 row_mask:0xf bank_mask:0xf
	v_cndmask_b32_e64 v109, v79, v85, s[38:39]
	v_mul_f32_e32 v75, v75, v83
	v_add_f32_e32 v82, 1.0, v82
	v_add_f32_e32 v83, 1.0, v88
	v_cndmask_b32_e64 v111, v78, v68, s[42:43]
	v_mov_b32_dpp v85, v109 row_ror:1 row_mask:0xf bank_mask:0xf
	v_rcp_f32_e32 v82, v82
	v_rcp_f32_e32 v83, v83
	v_mov_b32_dpp v192, v111 row_ror:15 row_mask:0xf bank_mask:0xf
	v_cndmask_b32_e64 v111, v79, v69, s[42:43]
	v_pk_mul_f32 v[84:85], v[136:137], v[84:85]
	v_cvt_pk_bf16_f32 v74, v74, v75
	v_mul_f32_e32 v75, v86, v82
	v_mov_b32_dpp v193, v111 row_ror:15 row_mask:0xf bank_mask:0xf
	v_pk_fma_f32 v[84:85], v[140:141], v[78:79], v[84:85]
	v_mul_f32_e32 v82, v87, v83
	v_pk_fma_f32 v[84:85], v[144:145], v[192:193], v[84:85]
	v_mad_i64_i32 v[76:77], s[12:13], v184, s7, v[76:77]
	v_pk_add_f32 v[84:85], v[132:133], v[84:85]
	v_lshl_add_u64 v[184:185], v[76:77], 0, v[194:195]
	v_mul_f32_e32 v75, v75, v84
	v_mul_f32_e32 v82, v82, v85
	v_cvt_pk_bf16_f32 v75, v75, v82
	global_store_dwordx2 v[184:185], v[74:75], off
	v_cndmask_b32_e64 v74, v72, v92, s[38:39]
	s_nop 1
	v_mov_b32_dpp v82, v74 row_ror:1 row_mask:0xf bank_mask:0xf
	v_cndmask_b32_e64 v74, v73, v93, s[38:39]
	v_cndmask_b32_e64 v75, v71, v91, s[38:39]
	s_nop 0
	v_mov_b32_dpp v83, v74 row_ror:1 row_mask:0xf bank_mask:0xf
	v_cndmask_b32_e64 v74, v70, v90, s[38:39]
	v_cndmask_b32_e64 v80, v66, v80, s[38:39]
	v_cndmask_b32_e64 v81, v67, v81, s[38:39]
	v_cndmask_b32_e64 v78, v68, v78, s[38:39]
	v_cndmask_b32_e64 v79, v69, v79, s[38:39]
	v_mov_b32_dpp v84, v74 row_ror:1 row_mask:0xf bank_mask:0xf
	v_mov_b32_dpp v85, v75 row_ror:1 row_mask:0xf bank_mask:0xf
	v_mov_b32_dpp v86, v80 row_ror:1 row_mask:0xf bank_mask:0xf
	v_mov_b32_dpp v87, v81 row_ror:1 row_mask:0xf bank_mask:0xf
	v_mov_b32_dpp v88, v78 row_ror:1 row_mask:0xf bank_mask:0xf
	v_mov_b32_dpp v89, v79 row_ror:1 row_mask:0xf bank_mask:0xf
	v_mov_b32_dpp v76, v72 row_ror:15 row_mask:0xf bank_mask:0xf
	v_mov_b32_dpp v77, v73 row_ror:15 row_mask:0xf bank_mask:0xf
	v_mov_b32_dpp v74, v70 row_ror:15 row_mask:0xf bank_mask:0xf
	v_mov_b32_dpp v75, v71 row_ror:15 row_mask:0xf bank_mask:0xf
	v_mov_b32_dpp v80, v66 row_ror:15 row_mask:0xf bank_mask:0xf
	v_mov_b32_dpp v81, v67 row_ror:15 row_mask:0xf bank_mask:0xf
	v_mov_b32_dpp v78, v68 row_ror:15 row_mask:0xf bank_mask:0xf
	v_mov_b32_dpp v79, v69 row_ror:15 row_mask:0xf bank_mask:0xf
	s_and_saveexec_b64 s[12:13], s[40:41]
	s_cbranch_execz .LBB0_769
	v_pk_mul_f32 v[82:83], v[122:123], v[82:83]
	v_pk_mul_f32 v[86:87], v[134:135], v[86:87]
	v_pk_fma_f32 v[82:83], v[126:127], v[72:73], v[82:83]
	v_pk_mul_f32 v[84:85], v[124:125], v[84:85]
	v_pk_fma_f32 v[76:77], v[118:119], v[76:77], v[82:83]
	v_pk_fma_f32 v[86:87], v[138:139], v[66:67], v[86:87]
	v_pk_add_f32 v[76:77], v[114:115], v[76:77]
	v_pk_fma_f32 v[84:85], v[128:129], v[70:71], v[84:85]
	v_mul_f32_e32 v82, 0xbfb8aa3b, v76
	v_exp_f32_e32 v82, v82
	v_mul_f32_e32 v83, 0xbfb8aa3b, v77
	v_exp_f32_e32 v83, v83
	v_pk_fma_f32 v[80:81], v[142:143], v[80:81], v[86:87]
	v_add_f32_e32 v82, 1.0, v82
	v_rcp_f32_e32 v82, v82
	v_pk_fma_f32 v[74:75], v[120:121], v[74:75], v[84:85]
	v_pk_add_f32 v[80:81], v[130:131], v[80:81]
	v_add_f32_e32 v83, 1.0, v83
	v_pk_add_f32 v[74:75], v[116:117], v[74:75]
	v_mul_f32_e32 v76, v76, v82
	v_rcp_f32_e32 v83, v83
	v_mul_f32_e32 v76, v76, v80
	v_mul_f32_e32 v80, 0xbfb8aa3b, v74
	v_mul_f32_e32 v82, 0xbfb8aa3b, v75
	v_exp_f32_e32 v80, v80
	v_exp_f32_e32 v82, v82
	v_mul_f32_e32 v77, v77, v83
	v_mul_f32_e32 v77, v77, v81
	v_add_f32_e32 v80, 1.0, v80
	v_add_f32_e32 v81, 1.0, v82
	v_rcp_f32_e32 v80, v80
	v_rcp_f32_e32 v81, v81
	v_pk_mul_f32 v[88:89], v[136:137], v[88:89]
	v_cvt_pk_bf16_f32 v76, v76, v77
	v_mul_f32_e32 v74, v74, v80
	v_pk_fma_f32 v[88:89], v[140:141], v[68:69], v[88:89]
	v_mul_f32_e32 v75, v75, v81
	v_pk_fma_f32 v[78:79], v[144:145], v[78:79], v[88:89]
	s_nop 0
	v_pk_add_f32 v[78:79], v[132:133], v[78:79]
	s_nop 0
	v_mul_f32_e32 v74, v74, v78
	v_mul_f32_e32 v75, v75, v79
	v_cvt_pk_bf16_f32 v77, v74, v75
	v_mov_b64_e32 v[74:75], s[30:31]
	v_mad_i64_i32 v[74:75], s[34:35], v174, s7, v[74:75]
	v_lshl_add_u64 v[74:75], v[178:179], 1, v[74:75]
	global_store_dwordx2 v[74:75], v[76:77], off

; __device__ __forceinline__ unsigned cvt_pk_bf16(float lo, float hi) { unsigned r; asm volatile("v_cvt_pk_bf16_f32 %0, %1, %2" : "=v"(r) : "v"(lo), "v"(hi)); return r; }
; __device__ __forceinline__ float sigmoid_f(float x) { return fast_rcp(1.0f + fast_exp2(-1.4426950409f * x)); }
;     __device__ __forceinline__ void operator()(f32x4 (&acc)[2][2][4][2], const Unit& u, int wr, int wc, int fr, int fq) const {
;     ...
;         for (int n = 0; n < 2; ++n) {
;             const int j4 = u.pn * 128 + wc * 32 + 8 * fq + 4 * n;
;             f32x4 kc[2][3], bc[2];
; #pragma unroll
;             for (int bj = 0; bj < 2; ++bj) { bc[bj] = *(const f32x4*)(cb + bj * FF + j4);
; #pragma unroll
;                 for (int w = 0; w < 3; ++w) kc[bj][w] = *(const f32x4*)(ck + w * NUP + bj * FF + j4); }
; #pragma unroll
;             for (int ai = 0; ai < 2; ++ai) {
;                 const int grp = u.pm * 4 + ai * 2 + wr;
; #pragma unroll
;                 for (int m = 0; m < 4; ++m) {
;                     f32x4 cv[2];
; #pragma unroll
;                     for (int bj = 0; bj < 2; ++bj) {
;                         const f32x4 cur = acc[ai][bj][m][n], lo = acc[ai][bj][m > 0 ? m - 1 : 0][n], hi = acc[ai][bj][m < 3 ? m + 1 : 3][n];
;                         f32x4 pv, nv;
; #pragma unroll
;                         for (int idx = 0; idx < 4; ++idx) {
;                             const float y = (fr == 15) ? lo[idx] : cur[idx], z = (fr == 0) ? hi[idx] : cur[idx];
;                             pv[idx] = __int_as_float(__builtin_amdgcn_update_dpp(0, __float_as_int(y), 0x121, 0xf, 0xf, false));
;                             nv[idx] = __int_as_float(__builtin_amdgcn_update_dpp(0, __float_as_int(z), 0x12f, 0xf, 0xf, false));
;                         }
;                         cv[bj] = kc[bj][0] * pv + kc[bj][1] * cur + kc[bj][2] * nv + bc[bj];
;                     }
;                     const int row = row0 + ai * HALF + m * 16;
;                     const bool edge = (m == 0 && fr == 0) || (m == 3 && fr == 15);
;                     if (!edge) { const f32x4 gt = cv[0], vl = cv[1];
;                         u32x2 w; w.x = cvt_pk_bf16(gt[0] * sigmoid_f(gt[0]) * vl[0], gt[1] * sigmoid_f(gt[1]) * vl[1]); w.y = cvt_pk_bf16(gt[2] * sigmoid_f(gt[2]) * vl[2], gt[3] * sigmoid_f(gt[3]) * vl[3]);
;                         *(u32x2*)(ACT + (size_t)row * FF + j4) = w; }
.LBB0_771:
	s_or_b64 exec, exec, s[12:13]
	global_load_dwordx4 v[66:69], v[202:203], off offset:16
	global_load_dwordx4 v[78:81], v[204:205], off offset:16
	global_load_dwordx4 v[74:77], v[206:207], off offset:3088
	global_load_dwordx4 v[70:73], v[210:211], off offset:2064
	global_load_dwordx4 v[82:85], v[214:215], off offset:1552
	global_load_dwordx4 v[94:97], v[216:217], off offset:1552
	global_load_dwordx4 v[90:93], v[218:219], off offset:528
	global_load_dwordx4 v[86:89], v[222:223], off offset:3600
	v_mov_b32_e32 v181, v180
	v_mov_b32_e32 v183, v182
	v_mov_b32_e32 v118, v180
	v_mov_b32_e32 v119, v180
	v_pk_mul_f32 v[120:121], v[64:65], v[118:119]
	v_pk_mul_f32 v[122:123], v[62:63], v[180:181]
	v_pk_mul_f32 v[64:65], v[56:57], v[118:119]
	v_pk_mul_f32 v[118:119], v[54:55], v[180:181]
	v_mov_b32_e32 v54, v182
	v_mov_b32_e32 v55, v182
	v_pk_mul_f32 v[58:59], v[58:59], v[182:183]
	v_pk_mul_f32 v[56:57], v[60:61], v[54:55]
	v_pk_mul_f32 v[52:53], v[52:53], v[54:55]
	v_pk_mul_f32 v[54:55], v[50:51], v[182:183]
	v_cndmask_b32_e64 v50, v122, v58, s[42:43]
	v_cndmask_b32_e64 v51, v120, v56, s[42:43]
	s_nop 0
	v_mov_b32_dpp v60, v50 row_ror:15 row_mask:0xf bank_mask:0xf
	v_cndmask_b32_e64 v50, v123, v59, s[42:43]
	v_cndmask_b32_e64 v109, v121, v57, s[42:43]
	s_nop 0
	v_mov_b32_dpp v61, v50 row_ror:15 row_mask:0xf bank_mask:0xf
	v_mov_b32_dpp v50, v51 row_ror:15 row_mask:0xf bank_mask:0xf
	v_mov_b32_dpp v51, v109 row_ror:15 row_mask:0xf bank_mask:0xf
	v_cndmask_b32_e64 v109, v118, v54, s[42:43]
	s_nop 1
	v_mov_b32_dpp v126, v109 row_ror:15 row_mask:0xf bank_mask:0xf
	v_cndmask_b32_e64 v109, v119, v55, s[42:43]
	s_nop 1
	v_mov_b32_dpp v127, v109 row_ror:15 row_mask:0xf bank_mask:0xf
	v_cndmask_b32_e64 v109, v64, v52, s[42:43]
	s_nop 1
	v_mov_b32_dpp v130, v109 row_ror:15 row_mask:0xf bank_mask:0xf
	v_cndmask_b32_e64 v109, v65, v53, s[42:43]
	v_mov_b32_dpp v62, v122 row_ror:1 row_mask:0xf bank_mask:0xf
	v_mov_b32_dpp v63, v123 row_ror:1 row_mask:0xf bank_mask:0xf
	v_mov_b32_dpp v124, v120 row_ror:1 row_mask:0xf bank_mask:0xf
	v_mov_b32_dpp v125, v121 row_ror:1 row_mask:0xf bank_mask:0xf
	v_mov_b32_dpp v128, v118 row_ror:1 row_mask:0xf bank_mask:0xf
	v_mov_b32_dpp v129, v119 row_ror:1 row_mask:0xf bank_mask:0xf
	v_mov_b32_dpp v132, v64 row_ror:1 row_mask:0xf bank_mask:0xf
	v_mov_b32_dpp v133, v65 row_ror:1 row_mask:0xf bank_mask:0xf
	v_mov_b32_dpp v131, v109 row_ror:15 row_mask:0xf bank_mask:0xf
	s_and_saveexec_b64 s[12:13], s[44:45]
	s_cbranch_execz .LBB0_773
	s_waitcnt vmcnt(6)
	v_pk_mul_f32 v[62:63], v[78:79], v[62:63]
	v_pk_mul_f32 v[124:125], v[80:81], v[124:125]
	s_waitcnt vmcnt(5)
	v_pk_fma_f32 v[62:63], v[122:123], v[74:75], v[62:63]
	v_pk_fma_f32 v[124:125], v[120:121], v[76:77], v[124:125]
	s_waitcnt vmcnt(4)
	v_pk_fma_f32 v[60:61], v[70:71], v[60:61], v[62:63]
	v_pk_fma_f32 v[50:51], v[72:73], v[50:51], v[124:125]
	v_pk_add_f32 v[60:61], v[66:67], v[60:61]
	v_pk_add_f32 v[50:51], v[68:69], v[50:51]
	v_mul_f32_e32 v62, 0xbfb8aa3b, v60
	v_mul_f32_e32 v63, 0xbfb8aa3b, v61
	v_exp_f32_e32 v62, v62
	v_exp_f32_e32 v63, v63
	s_waitcnt vmcnt(2)
	v_pk_mul_f32 v[132:133], v[96:97], v[132:133]
	v_pk_mul_f32 v[128:129], v[94:95], v[128:129]
	v_add_f32_e32 v62, 1.0, v62
	v_add_f32_e32 v63, 1.0, v63
	v_rcp_f32_e32 v62, v62
	v_rcp_f32_e32 v63, v63
	s_waitcnt vmcnt(1)
	v_pk_fma_f32 v[132:133], v[64:65], v[92:93], v[132:133]
	v_pk_fma_f32 v[128:129], v[118:119], v[90:91], v[128:129]
	v_mul_f32_e32 v60, v60, v62
	v_mul_f32_e32 v61, v61, v63
	v_mul_f32_e32 v62, 0xbfb8aa3b, v50
	v_mul_f32_e32 v63, 0xbfb8aa3b, v51
	v_exp_f32_e32 v62, v62
	v_exp_f32_e32 v63, v63
	s_waitcnt vmcnt(0)
	v_pk_fma_f32 v[130:131], v[88:89], v[130:131], v[132:133]
	v_pk_fma_f32 v[126:127], v[86:87], v[126:127], v[128:129]
	v_add_f32_e32 v62, 1.0, v62
	v_add_f32_e32 v63, 1.0, v63
	v_rcp_f32_e32 v62, v62
	v_rcp_f32_e32 v63, v63
	v_pk_add_f32 v[126:127], v[82:83], v[126:127]
	v_pk_add_f32 v[128:129], v[84:85], v[130:131]
	v_mul_f32_e32 v50, v50, v62
	v_mul_f32_e32 v51, v51, v63
	v_mul_f32_e32 v60, v60, v126
	v_mul_f32_e32 v61, v61, v127
	v_mul_f32_e32 v50, v50, v128
	v_mul_f32_e32 v51, v51, v129
	v_cvt_pk_bf16_f32 v60, v60, v61
	v_cvt_pk_bf16_f32 v61, v50, v51
	v_mov_b64_e32 v[50:51], s[30:31]
	v_mad_i64_i32 v[50:51], s[16:17], v176, s7, v[50:51]
	v_lshl_add_u64 v[50:51], v[178:179], 1, v[50:51]
	global_store_dwordx2 v[50:51], v[60:61], off offset:8

; __device__ __forceinline__ unsigned cvt_pk_bf16(float lo, float hi) { unsigned r; asm volatile("v_cvt_pk_bf16_f32 %0, %1, %2" : "=v"(r) : "v"(lo), "v"(hi)); return r; }
; __device__ __forceinline__ float sigmoid_f(float x) { return fast_rcp(1.0f + fast_exp2(-1.4426950409f * x)); }
;     __device__ __forceinline__ void operator()(f32x4 (&acc)[2][2][4][2], const Unit& u, int wr, int wc, int fr, int fq) const {
;     ...
;                     f32x4 cv[2];
; #pragma unroll
;                     for (int bj = 0; bj < 2; ++bj) {
;                         const f32x4 cur = acc[ai][bj][m][n], lo = acc[ai][bj][m > 0 ? m - 1 : 0][n], hi = acc[ai][bj][m < 3 ? m + 1 : 3][n];
;                         f32x4 pv, nv;
; #pragma unroll
;                         for (int idx = 0; idx < 4; ++idx) {
;                             const float y = (fr == 15) ? lo[idx] : cur[idx], z = (fr == 0) ? hi[idx] : cur[idx];
;                             pv[idx] = __int_as_float(__builtin_amdgcn_update_dpp(0, __float_as_int(y), 0x121, 0xf, 0xf, false));
;                             nv[idx] = __int_as_float(__builtin_amdgcn_update_dpp(0, __float_as_int(z), 0x12f, 0xf, 0xf, false));
;                         }
;                         cv[bj] = kc[bj][0] * pv + kc[bj][1] * cur + kc[bj][2] * nv + bc[bj];
;                     }
;                     const int row = row0 + ai * HALF + m * 16;
;                     const bool edge = (m == 0 && fr == 0) || (m == 3 && fr == 15);
;                     if (!edge) { const f32x4 gt = cv[0], vl = cv[1];
;                         u32x2 w; w.x = cvt_pk_bf16(gt[0] * sigmoid_f(gt[0]) * vl[0], gt[1] * sigmoid_f(gt[1]) * vl[1]); w.y = cvt_pk_bf16(gt[2] * sigmoid_f(gt[2]) * vl[2], gt[3] * sigmoid_f(gt[3]) * vl[3]);
;                         *(u32x2*)(ACT + (size_t)row * FF + j4) = w; }
.LBB0_775:
	s_or_b64 exec, exec, s[12:13]
	v_mov_b32_e32 v229, v228
	v_mov_b32_e32 v124, v228
	v_mov_b32_e32 v125, v228
	v_mov_b32_e32 v231, v230
	v_pk_mul_f32 v[60:61], v[48:49], v[124:125]
	v_pk_mul_f32 v[62:63], v[46:47], v[228:229]
	v_pk_mul_f32 v[46:47], v[40:41], v[124:125]
	v_mov_b32_e32 v124, v230
	v_mov_b32_e32 v125, v230
	v_pk_mul_f32 v[48:49], v[38:39], v[228:229]
	v_pk_mul_f32 v[38:39], v[44:45], v[124:125]
	v_pk_mul_f32 v[40:41], v[42:43], v[230:231]
	v_cndmask_b32_e64 v43, v58, v122, s[38:39]
	v_cndmask_b32_e64 v45, v58, v62, s[42:43]
	v_cndmask_b32_e64 v109, v59, v63, s[42:43]
	v_mov_b32_dpp v42, v43 row_ror:1 row_mask:0xf bank_mask:0xf
	v_mov_b32_dpp v44, v45 row_ror:15 row_mask:0xf bank_mask:0xf
	v_cndmask_b32_e64 v45, v59, v123, s[38:39]
	v_cndmask_b32_e64 v111, v56, v60, s[42:43]
	s_nop 0
	v_mov_b32_dpp v43, v45 row_ror:1 row_mask:0xf bank_mask:0xf
	s_waitcnt vmcnt(6)
	v_pk_mul_f32 v[42:43], v[78:79], v[42:43]
	v_mov_b32_dpp v122, v111 row_ror:15 row_mask:0xf bank_mask:0xf
	v_mov_b32_dpp v45, v109 row_ror:15 row_mask:0xf bank_mask:0xf
	v_cndmask_b32_e64 v109, v56, v120, s[38:39]
	v_cndmask_b32_e64 v111, v57, v61, s[42:43]
	s_nop 0
	v_mov_b32_dpp v120, v109 row_ror:1 row_mask:0xf bank_mask:0xf
	v_cndmask_b32_e64 v109, v57, v121, s[38:39]
	s_waitcnt vmcnt(5)
	v_pk_fma_f32 v[42:43], v[58:59], v[74:75], v[42:43]
	v_pk_mul_f32 v[36:37], v[36:37], v[124:125]
	v_mov_b32_dpp v121, v109 row_ror:1 row_mask:0xf bank_mask:0xf
	v_cndmask_b32_e64 v109, v54, v118, s[38:39]
	v_mov_b32_dpp v123, v111 row_ror:15 row_mask:0xf bank_mask:0xf
	v_cndmask_b32_e64 v111, v54, v48, s[42:43]
	v_mov_b32_dpp v118, v109 row_ror:1 row_mask:0xf bank_mask:0xf
	v_cndmask_b32_e64 v109, v55, v119, s[38:39]
	s_waitcnt vmcnt(4)
	v_pk_fma_f32 v[42:43], v[70:71], v[44:45], v[42:43]
	v_mov_b32_dpp v124, v111 row_ror:15 row_mask:0xf bank_mask:0xf
	v_cndmask_b32_e64 v111, v55, v49, s[42:43]
	v_mov_b32_dpp v119, v109 row_ror:1 row_mask:0xf bank_mask:0xf
	v_cndmask_b32_e64 v109, v52, v64, s[38:39]
	v_pk_add_f32 v[42:43], v[66:67], v[42:43]
	v_mov_b32_dpp v125, v111 row_ror:15 row_mask:0xf bank_mask:0xf
	v_cndmask_b32_e64 v111, v52, v46, s[42:43]
	v_mov_b32_dpp v64, v109 row_ror:1 row_mask:0xf bank_mask:0xf
	v_cndmask_b32_e64 v109, v53, v65, s[38:39]
	v_mul_f32_e32 v44, 0xbfb8aa3b, v42
	v_mov_b32_dpp v126, v111 row_ror:15 row_mask:0xf bank_mask:0xf
	v_cndmask_b32_e64 v111, v53, v47, s[42:43]
	v_mov_b32_dpp v65, v109 row_ror:1 row_mask:0xf bank_mask:0xf
	v_exp_f32_e32 v109, v44
	v_mul_f32_e32 v44, 0xbfb8aa3b, v43
	v_mov_b32_dpp v127, v111 row_ror:15 row_mask:0xf bank_mask:0xf
	v_exp_f32_e32 v111, v44
	v_add_f32_e32 v109, 1.0, v109
	v_pk_mul_f32 v[120:121], v[80:81], v[120:121]
	v_rcp_f32_e32 v109, v109
	v_add_f32_e32 v111, 1.0, v111
	v_pk_fma_f32 v[120:121], v[56:57], v[76:77], v[120:121]
	v_rcp_f32_e32 v111, v111
	v_pk_fma_f32 v[44:45], v[72:73], v[122:123], v[120:121]
	v_mul_f32_e32 v42, v42, v109
	v_pk_add_f32 v[44:45], v[68:69], v[44:45]
	v_mul_f32_e32 v43, v43, v111
	v_mul_f32_e32 v109, 0xbfb8aa3b, v44
	v_exp_f32_e32 v109, v109
	v_mul_f32_e32 v111, 0xbfb8aa3b, v45
	v_exp_f32_e32 v111, v111
	s_waitcnt vmcnt(2)
	v_pk_mul_f32 v[118:119], v[94:95], v[118:119]
	v_add_f32_e32 v109, 1.0, v109
	s_waitcnt vmcnt(1)
	v_pk_fma_f32 v[118:119], v[54:55], v[90:91], v[118:119]
	v_rcp_f32_e32 v109, v109
	v_add_f32_e32 v111, 1.0, v111
	v_pk_mul_f32 v[64:65], v[96:97], v[64:65]
	s_waitcnt vmcnt(0)
	v_pk_fma_f32 v[118:119], v[86:87], v[124:125], v[118:119]
	v_rcp_f32_e32 v111, v111
	v_pk_fma_f32 v[64:65], v[52:53], v[92:93], v[64:65]
	v_pk_add_f32 v[118:119], v[82:83], v[118:119]
	v_pk_fma_f32 v[64:65], v[88:89], v[126:127], v[64:65]
	v_mul_f32_e32 v42, v42, v118
	v_mul_f32_e32 v43, v43, v119
	v_pk_add_f32 v[64:65], v[84:85], v[64:65]
	v_cvt_pk_bf16_f32 v42, v42, v43
	v_mul_f32_e32 v43, v44, v109
	v_mul_f32_e32 v43, v43, v64
	v_mul_f32_e32 v44, v45, v111
	v_mul_f32_e32 v44, v44, v65
	v_cvt_pk_bf16_f32 v43, v43, v44
	global_store_dwordx2 v[104:105], v[42:43], off offset:8
	v_cndmask_b32_e64 v43, v62, v58, s[38:39]
	v_cndmask_b32_e64 v45, v62, v40, s[42:43]
	v_cndmask_b32_e64 v58, v63, v41, s[42:43]
	v_mov_b32_dpp v42, v43 row_ror:1 row_mask:0xf bank_mask:0xf
	v_mov_b32_dpp v44, v45 row_ror:15 row_mask:0xf bank_mask:0xf
	v_cndmask_b32_e64 v45, v63, v59, s[38:39]
	v_cndmask_b32_e64 v59, v60, v38, s[42:43]
	v_cndmask_b32_e64 v64, v61, v39, s[42:43]
	v_mov_b32_dpp v43, v45 row_ror:1 row_mask:0xf bank_mask:0xf
	v_pk_mul_f32 v[34:35], v[34:35], v[230:231]
	v_pk_mul_f32 v[42:43], v[78:79], v[42:43]
	v_mov_b32_dpp v45, v58 row_ror:15 row_mask:0xf bank_mask:0xf
	v_cndmask_b32_e64 v58, v60, v56, s[38:39]
	v_cndmask_b32_e64 v65, v48, v34, s[42:43]
	v_pk_fma_f32 v[42:43], v[62:63], v[74:75], v[42:43]
	v_mov_b32_dpp v56, v58 row_ror:1 row_mask:0xf bank_mask:0xf
	v_pk_fma_f32 v[42:43], v[70:71], v[44:45], v[42:43]
	v_cndmask_b32_e64 v104, v49, v35, s[42:43]
	v_mov_b32_dpp v58, v59 row_ror:15 row_mask:0xf bank_mask:0xf
	v_cndmask_b32_e64 v59, v61, v57, s[38:39]
	v_pk_add_f32 v[42:43], v[66:67], v[42:43]
	v_cndmask_b32_e64 v105, v46, v36, s[42:43]
	v_mov_b32_dpp v57, v59 row_ror:1 row_mask:0xf bank_mask:0xf
	v_mul_f32_e32 v44, 0xbfb8aa3b, v42
	v_pk_mul_f32 v[56:57], v[80:81], v[56:57]
; __device__ __forceinline__ unsigned cvt_pk_bf16(float lo, float hi) { unsigned r; asm volatile("v_cvt_pk_bf16_f32 %0, %1, %2" : "=v"(r) : "v"(lo), "v"(hi)); return r; }
; __device__ __forceinline__ float sigmoid_f(float x) { return fast_rcp(1.0f + fast_exp2(-1.4426950409f * x)); }
;     __device__ __forceinline__ void operator()(f32x4 (&acc)[2][2][4][2], const Unit& u, int wr, int wc, int fr, int fq) const {
;     ...
;                     f32x4 cv[2];
; #pragma unroll
;                     for (int bj = 0; bj < 2; ++bj) {
;                         const f32x4 cur = acc[ai][bj][m][n], lo = acc[ai][bj][m > 0 ? m - 1 : 0][n], hi = acc[ai][bj][m < 3 ? m + 1 : 3][n];
;                         f32x4 pv, nv;
; #pragma unroll
;                         for (int idx = 0; idx < 4; ++idx) {
;                             const float y = (fr == 15) ? lo[idx] : cur[idx], z = (fr == 0) ? hi[idx] : cur[idx];
;                             pv[idx] = __int_as_float(__builtin_amdgcn_update_dpp(0, __float_as_int(y), 0x121, 0xf, 0xf, false));
;                             nv[idx] = __int_as_float(__builtin_amdgcn_update_dpp(0, __float_as_int(z), 0x12f, 0xf, 0xf, false));
;                         }
;                         cv[bj] = kc[bj][0] * pv + kc[bj][1] * cur + kc[bj][2] * nv + bc[bj];
;                     }
;                     const int row = row0 + ai * HALF + m * 16;
;                     const bool edge = (m == 0 && fr == 0) || (m == 3 && fr == 15);
;                     if (!edge) { const f32x4 gt = cv[0], vl = cv[1];
;                         u32x2 w; w.x = cvt_pk_bf16(gt[0] * sigmoid_f(gt[0]) * vl[0], gt[1] * sigmoid_f(gt[1]) * vl[1]); w.y = cvt_pk_bf16(gt[2] * sigmoid_f(gt[2]) * vl[2], gt[3] * sigmoid_f(gt[3]) * vl[3]);
;                         *(u32x2*)(ACT + (size_t)row * FF + j4) = w; }
	v_mov_b32_dpp v59, v64 row_ror:15 row_mask:0xf bank_mask:0xf
	v_cndmask_b32_e64 v64, v48, v54, s[38:39]
	v_pk_fma_f32 v[56:57], v[60:61], v[76:77], v[56:57]
	v_cndmask_b32_e64 v109, v47, v37, s[42:43]
	v_mov_b32_dpp v54, v64 row_ror:1 row_mask:0xf bank_mask:0xf
	s_nop 1
	v_mov_b32_dpp v64, v65 row_ror:15 row_mask:0xf bank_mask:0xf
	v_cndmask_b32_e64 v65, v49, v55, s[38:39]
	s_nop 1
	v_mov_b32_dpp v55, v65 row_ror:1 row_mask:0xf bank_mask:0xf
	v_pk_mul_f32 v[54:55], v[94:95], v[54:55]
	s_nop 0
	v_mov_b32_dpp v65, v104 row_ror:15 row_mask:0xf bank_mask:0xf
	v_pk_fma_f32 v[54:55], v[48:49], v[90:91], v[54:55]
	v_cndmask_b32_e64 v104, v46, v52, s[38:39]
	v_pk_fma_f32 v[54:55], v[86:87], v[64:65], v[54:55]
	v_exp_f32_e32 v64, v44
	v_mul_f32_e32 v44, 0xbfb8aa3b, v43
	v_exp_f32_e32 v65, v44
	v_pk_fma_f32 v[44:45], v[72:73], v[58:59], v[56:57]
	v_add_f32_e32 v56, 1.0, v64
	v_rcp_f32_e32 v56, v56
	v_pk_add_f32 v[54:55], v[82:83], v[54:55]
	v_pk_add_f32 v[44:45], v[68:69], v[44:45]
	v_add_f32_e32 v57, 1.0, v65
	v_mul_f32_e32 v42, v42, v56
	v_mul_f32_e32 v42, v42, v54
	v_mul_f32_e32 v54, 0xbfb8aa3b, v44
	v_rcp_f32_e32 v57, v57
	v_exp_f32_e32 v54, v54
	v_mul_f32_e32 v56, 0xbfb8aa3b, v45
	v_exp_f32_e32 v56, v56
	v_mul_f32_e32 v43, v43, v57
	v_add_f32_e32 v54, 1.0, v54
	v_mov_b32_dpp v52, v104 row_ror:1 row_mask:0xf bank_mask:0xf
	v_mul_f32_e32 v43, v43, v55
	v_rcp_f32_e32 v54, v54
	v_mov_b32_dpp v104, v105 row_ror:15 row_mask:0xf bank_mask:0xf
	v_cndmask_b32_e64 v105, v47, v53, s[38:39]
	v_add_f32_e32 v55, 1.0, v56
	v_rcp_f32_e32 v55, v55
	v_mov_b32_dpp v53, v105 row_ror:1 row_mask:0xf bank_mask:0xf
	v_pk_mul_f32 v[52:53], v[96:97], v[52:53]
	v_cvt_pk_bf16_f32 v42, v42, v43
	v_mul_f32_e32 v43, v44, v54
	v_mov_b32_dpp v105, v109 row_ror:15 row_mask:0xf bank_mask:0xf
	v_pk_fma_f32 v[52:53], v[46:47], v[92:93], v[52:53]
	v_mul_f32_e32 v44, v45, v55
	v_pk_fma_f32 v[52:53], v[88:89], v[104:105], v[52:53]
	v_pk_add_f32 v[52:53], v[84:85], v[52:53]
	v_mul_f32_e32 v43, v43, v52
	v_mul_f32_e32 v44, v44, v53
	v_cvt_pk_bf16_f32 v43, v43, v44
	global_store_dwordx2 v[106:107], v[42:43], off offset:8
	v_cndmask_b32_e64 v42, v40, v62, s[38:39]
	v_cndmask_b32_e64 v43, v39, v61, s[38:39]
	s_nop 0
	v_mov_b32_dpp v52, v42 row_ror:1 row_mask:0xf bank_mask:0xf
	v_cndmask_b32_e64 v42, v41, v63, s[38:39]
	v_cndmask_b32_e64 v48, v34, v48, s[38:39]
	s_nop 0
	v_mov_b32_dpp v53, v42 row_ror:1 row_mask:0xf bank_mask:0xf
	v_cndmask_b32_e64 v42, v38, v60, s[38:39]
	v_cndmask_b32_e64 v49, v35, v49, s[38:39]
	v_cndmask_b32_e64 v46, v36, v46, s[38:39]
	v_cndmask_b32_e64 v47, v37, v47, s[38:39]
	v_mov_b32_dpp v54, v42 row_ror:1 row_mask:0xf bank_mask:0xf
	v_mov_b32_dpp v55, v43 row_ror:1 row_mask:0xf bank_mask:0xf
	v_mov_b32_dpp v56, v48 row_ror:1 row_mask:0xf bank_mask:0xf
	v_mov_b32_dpp v57, v49 row_ror:1 row_mask:0xf bank_mask:0xf
	v_mov_b32_dpp v58, v46 row_ror:1 row_mask:0xf bank_mask:0xf
	v_mov_b32_dpp v59, v47 row_ror:1 row_mask:0xf bank_mask:0xf
	v_mov_b32_dpp v44, v40 row_ror:15 row_mask:0xf bank_mask:0xf
	v_mov_b32_dpp v45, v41 row_ror:15 row_mask:0xf bank_mask:0xf
	v_mov_b32_dpp v42, v38 row_ror:15 row_mask:0xf bank_mask:0xf
	v_mov_b32_dpp v43, v39 row_ror:15 row_mask:0xf bank_mask:0xf
	v_mov_b32_dpp v48, v34 row_ror:15 row_mask:0xf bank_mask:0xf
	v_mov_b32_dpp v49, v35 row_ror:15 row_mask:0xf bank_mask:0xf
	v_mov_b32_dpp v46, v36 row_ror:15 row_mask:0xf bank_mask:0xf
	v_mov_b32_dpp v47, v37 row_ror:15 row_mask:0xf bank_mask:0xf
	s_and_saveexec_b64 s[12:13], s[40:41]
	s_cbranch_execz .LBB0_777
	v_pk_mul_f32 v[52:53], v[78:79], v[52:53]
	v_pk_mul_f32 v[56:57], v[94:95], v[56:57]
	v_pk_fma_f32 v[52:53], v[40:41], v[74:75], v[52:53]
	v_pk_mul_f32 v[54:55], v[80:81], v[54:55]
	v_pk_fma_f32 v[44:45], v[70:71], v[44:45], v[52:53]
	v_pk_fma_f32 v[56:57], v[34:35], v[90:91], v[56:57]
	v_pk_add_f32 v[44:45], v[66:67], v[44:45]
	v_pk_fma_f32 v[54:55], v[38:39], v[76:77], v[54:55]
	v_mul_f32_e32 v52, 0xbfb8aa3b, v44
	v_exp_f32_e32 v52, v52
	v_mul_f32_e32 v53, 0xbfb8aa3b, v45
	v_exp_f32_e32 v53, v53
	v_pk_fma_f32 v[48:49], v[86:87], v[48:49], v[56:57]
	v_add_f32_e32 v52, 1.0, v52
	v_rcp_f32_e32 v52, v52
	v_pk_fma_f32 v[42:43], v[72:73], v[42:43], v[54:55]
	v_pk_add_f32 v[48:49], v[82:83], v[48:49]
	v_add_f32_e32 v53, 1.0, v53
	v_pk_add_f32 v[42:43], v[68:69], v[42:43]
	v_mul_f32_e32 v44, v44, v52
	v_rcp_f32_e32 v53, v53
	v_mul_f32_e32 v44, v44, v48
	v_mul_f32_e32 v48, 0xbfb8aa3b, v42
	v_mul_f32_e32 v52, 0xbfb8aa3b, v43
	v_exp_f32_e32 v48, v48
	v_exp_f32_e32 v52, v52
	v_mul_f32_e32 v45, v45, v53
	v_mul_f32_e32 v45, v45, v49
	v_add_f32_e32 v48, 1.0, v48
	v_add_f32_e32 v49, 1.0, v52
	v_rcp_f32_e32 v48, v48
	v_rcp_f32_e32 v49, v49
	v_pk_mul_f32 v[58:59], v[96:97], v[58:59]
	v_cvt_pk_bf16_f32 v44, v44, v45
	v_mul_f32_e32 v42, v42, v48
	v_pk_fma_f32 v[58:59], v[36:37], v[92:93], v[58:59]
	v_mul_f32_e32 v43, v43, v49
	v_pk_fma_f32 v[46:47], v[88:89], v[46:47], v[58:59]
	s_nop 0
	v_pk_add_f32 v[46:47], v[84:85], v[46:47]
	s_nop 0
	v_mul_f32_e32 v42, v42, v46
	v_mul_f32_e32 v43, v43, v47
	v_cvt_pk_bf16_f32 v45, v42, v43
	v_mov_b64_e32 v[42:43], s[30:31]
	v_mad_i64_i32 v[42:43], s[16:17], v160, s7, v[42:43]
	v_lshl_add_u64 v[42:43], v[178:179], 1, v[42:43]
	global_store_dwordx2 v[42:43], v[44:45], off offset:8

; __device__ __forceinline__ unsigned cvt_pk_bf16(float lo, float hi) { unsigned r; asm volatile("v_cvt_pk_bf16_f32 %0, %1, %2" : "=v"(r) : "v"(lo), "v"(hi)); return r; }
; __device__ __forceinline__ float sigmoid_f(float x) { return fast_rcp(1.0f + fast_exp2(-1.4426950409f * x)); }
;     __device__ __forceinline__ void operator()(f32x4 (&acc)[2][2][4][2], const Unit& u, int wr, int wc, int fr, int fq) const {
;     ...
;                     f32x4 cv[2];
; #pragma unroll
;                     for (int bj = 0; bj < 2; ++bj) {
;                         const f32x4 cur = acc[ai][bj][m][n], lo = acc[ai][bj][m > 0 ? m - 1 : 0][n], hi = acc[ai][bj][m < 3 ? m + 1 : 3][n];
;                         f32x4 pv, nv;
; #pragma unroll
;                         for (int idx = 0; idx < 4; ++idx) {
;                             const float y = (fr == 15) ? lo[idx] : cur[idx], z = (fr == 0) ? hi[idx] : cur[idx];
;                             pv[idx] = __int_as_float(__builtin_amdgcn_update_dpp(0, __float_as_int(y), 0x121, 0xf, 0xf, false));
;                             nv[idx] = __int_as_float(__builtin_amdgcn_update_dpp(0, __float_as_int(z), 0x12f, 0xf, 0xf, false));
;                         }
;                         cv[bj] = kc[bj][0] * pv + kc[bj][1] * cur + kc[bj][2] * nv + bc[bj];
;                     }
;                     const int row = row0 + ai * HALF + m * 16;
;                     const bool edge = (m == 0 && fr == 0) || (m == 3 && fr == 15);
;                     if (!edge) { const f32x4 gt = cv[0], vl = cv[1];
;                         u32x2 w; w.x = cvt_pk_bf16(gt[0] * sigmoid_f(gt[0]) * vl[0], gt[1] * sigmoid_f(gt[1]) * vl[1]); w.y = cvt_pk_bf16(gt[2] * sigmoid_f(gt[2]) * vl[2], gt[3] * sigmoid_f(gt[3]) * vl[3]);
;                         *(u32x2*)(ACT + (size_t)row * FF + j4) = w; }
.LBB0_779:
	s_or_b64 exec, exec, s[12:13]
	v_mov_b32_e32 v109, v108
	v_mov_b32_e32 v111, v110
	v_mov_b32_e32 v38, v108
	v_mov_b32_e32 v39, v108
	v_pk_mul_f32 v[34:35], v[32:33], v[38:39]
	v_pk_mul_f32 v[36:37], v[30:31], v[108:109]
	v_pk_mul_f32 v[30:31], v[24:25], v[38:39]
	v_mov_b32_e32 v38, v110
	v_mov_b32_e32 v39, v110
	v_pk_mul_f32 v[24:25], v[26:27], v[110:111]
	v_pk_mul_f32 v[32:33], v[22:23], v[108:109]
	v_pk_mul_f32 v[22:23], v[28:29], v[38:39]
	v_cndmask_b32_e64 v26, v36, v24, s[42:43]
	v_cndmask_b32_e64 v27, v34, v22, s[42:43]
	s_nop 0
	v_mov_b32_dpp v28, v26 row_ror:15 row_mask:0xf bank_mask:0xf
	v_cndmask_b32_e64 v26, v37, v25, s[42:43]
	v_pk_mul_f32 v[18:19], v[18:19], v[110:111]
	v_cndmask_b32_e64 v42, v35, v23, s[42:43]
	v_mov_b32_dpp v29, v26 row_ror:15 row_mask:0xf bank_mask:0xf
	v_cndmask_b32_e64 v43, v32, v18, s[42:43]
	v_pk_mul_f32 v[20:21], v[20:21], v[38:39]
	v_mov_b32_dpp v26, v27 row_ror:15 row_mask:0xf bank_mask:0xf
	v_cndmask_b32_e64 v46, v33, v19, s[42:43]
	v_cndmask_b32_e64 v47, v30, v20, s[42:43]
	v_mov_b32_dpp v27, v42 row_ror:15 row_mask:0xf bank_mask:0xf
	v_mov_b32_dpp v42, v43 row_ror:15 row_mask:0xf bank_mask:0xf
	v_mov_b32_dpp v43, v46 row_ror:15 row_mask:0xf bank_mask:0xf
	v_mov_b32_dpp v46, v47 row_ror:15 row_mask:0xf bank_mask:0xf
	v_cndmask_b32_e64 v52, v31, v21, s[42:43]
	v_mov_b32_dpp v38, v36 row_ror:1 row_mask:0xf bank_mask:0xf
	v_mov_b32_dpp v39, v37 row_ror:1 row_mask:0xf bank_mask:0xf
	v_mov_b32_dpp v40, v34 row_ror:1 row_mask:0xf bank_mask:0xf
	v_mov_b32_dpp v41, v35 row_ror:1 row_mask:0xf bank_mask:0xf
	v_mov_b32_dpp v44, v32 row_ror:1 row_mask:0xf bank_mask:0xf
	v_mov_b32_dpp v45, v33 row_ror:1 row_mask:0xf bank_mask:0xf
	v_mov_b32_dpp v48, v30 row_ror:1 row_mask:0xf bank_mask:0xf
	v_mov_b32_dpp v49, v31 row_ror:1 row_mask:0xf bank_mask:0xf
	v_mov_b32_dpp v47, v52 row_ror:15 row_mask:0xf bank_mask:0xf
	s_and_saveexec_b64 s[12:13], s[44:45]
	s_cbranch_execz .LBB0_781
	v_pk_mul_f32 v[38:39], v[78:79], v[38:39]
	v_pk_mul_f32 v[40:41], v[80:81], v[40:41]
	v_pk_fma_f32 v[38:39], v[36:37], v[74:75], v[38:39]
	v_pk_fma_f32 v[40:41], v[34:35], v[76:77], v[40:41]
	v_pk_fma_f32 v[28:29], v[70:71], v[28:29], v[38:39]
	v_pk_fma_f32 v[26:27], v[72:73], v[26:27], v[40:41]
	v_pk_add_f32 v[28:29], v[66:67], v[28:29]
	v_pk_add_f32 v[26:27], v[68:69], v[26:27]
	v_mul_f32_e32 v38, 0xbfb8aa3b, v28
	v_mul_f32_e32 v39, 0xbfb8aa3b, v29
	v_exp_f32_e32 v38, v38
	v_exp_f32_e32 v39, v39
	v_pk_mul_f32 v[48:49], v[96:97], v[48:49]
	v_pk_mul_f32 v[44:45], v[94:95], v[44:45]
	v_add_f32_e32 v38, 1.0, v38
	v_add_f32_e32 v39, 1.0, v39
	v_rcp_f32_e32 v38, v38
	v_rcp_f32_e32 v39, v39
	v_pk_fma_f32 v[48:49], v[30:31], v[92:93], v[48:49]
	v_pk_fma_f32 v[44:45], v[32:33], v[90:91], v[44:45]
	v_mul_f32_e32 v28, v28, v38
	v_mul_f32_e32 v29, v29, v39
	v_mul_f32_e32 v38, 0xbfb8aa3b, v26
	v_mul_f32_e32 v39, 0xbfb8aa3b, v27
	v_exp_f32_e32 v38, v38
	v_exp_f32_e32 v39, v39
	v_pk_fma_f32 v[46:47], v[88:89], v[46:47], v[48:49]
	v_pk_fma_f32 v[42:43], v[86:87], v[42:43], v[44:45]
	v_add_f32_e32 v38, 1.0, v38
	v_add_f32_e32 v39, 1.0, v39
	v_rcp_f32_e32 v38, v38
	v_rcp_f32_e32 v39, v39
	v_pk_add_f32 v[42:43], v[82:83], v[42:43]
	v_pk_add_f32 v[44:45], v[84:85], v[46:47]
	v_mul_f32_e32 v26, v26, v38
	v_mul_f32_e32 v27, v27, v39
	v_mul_f32_e32 v28, v28, v42
	v_mul_f32_e32 v29, v29, v43
	v_mul_f32_e32 v26, v26, v44
	v_mul_f32_e32 v27, v27, v45
	v_cvt_pk_bf16_f32 v28, v28, v29
	v_cvt_pk_bf16_f32 v29, v26, v27
	v_mov_b64_e32 v[26:27], s[30:31]
	v_mad_i64_i32 v[26:27], s[16:17], v158, s7, v[26:27]
	v_lshl_add_u64 v[26:27], v[178:179], 1, v[26:27]
	global_store_dwordx2 v[26:27], v[28:29], off offset:8

; __device__ __forceinline__ unsigned cvt_pk_bf16(float lo, float hi) { unsigned r; asm volatile("v_cvt_pk_bf16_f32 %0, %1, %2" : "=v"(r) : "v"(lo), "v"(hi)); return r; }
; __device__ __forceinline__ float sigmoid_f(float x) { return fast_rcp(1.0f + fast_exp2(-1.4426950409f * x)); }
;     __device__ __forceinline__ void operator()(f32x4 (&acc)[2][2][4][2], const Unit& u, int wr, int wc, int fr, int fq) const {
;     ...
;                     f32x4 cv[2];
; #pragma unroll
;                     for (int bj = 0; bj < 2; ++bj) {
;                         const f32x4 cur = acc[ai][bj][m][n], lo = acc[ai][bj][m > 0 ? m - 1 : 0][n], hi = acc[ai][bj][m < 3 ? m + 1 : 3][n];
;                         f32x4 pv, nv;
; #pragma unroll
;                         for (int idx = 0; idx < 4; ++idx) {
;                             const float y = (fr == 15) ? lo[idx] : cur[idx], z = (fr == 0) ? hi[idx] : cur[idx];
;                             pv[idx] = __int_as_float(__builtin_amdgcn_update_dpp(0, __float_as_int(y), 0x121, 0xf, 0xf, false));
;                             nv[idx] = __int_as_float(__builtin_amdgcn_update_dpp(0, __float_as_int(z), 0x12f, 0xf, 0xf, false));
;                         }
;                         cv[bj] = kc[bj][0] * pv + kc[bj][1] * cur + kc[bj][2] * nv + bc[bj];
;                     }
;                     const int row = row0 + ai * HALF + m * 16;
;                     const bool edge = (m == 0 && fr == 0) || (m == 3 && fr == 15);
;                     if (!edge) { const f32x4 gt = cv[0], vl = cv[1];
;                         u32x2 w; w.x = cvt_pk_bf16(gt[0] * sigmoid_f(gt[0]) * vl[0], gt[1] * sigmoid_f(gt[1]) * vl[1]); w.y = cvt_pk_bf16(gt[2] * sigmoid_f(gt[2]) * vl[2], gt[3] * sigmoid_f(gt[3]) * vl[3]);
;                         *(u32x2*)(ACT + (size_t)row * FF + j4) = w; }
.LBB0_783:
	s_or_b64 exec, exec, s[12:13]
	v_mov_b32_e32 v189, v188
	v_mov_b32_e32 v38, v188
	v_mov_b32_e32 v39, v188
	v_mov_b32_e32 v191, v190
	v_pk_mul_f32 v[26:27], v[16:17], v[38:39]
	v_pk_mul_f32 v[28:29], v[14:15], v[188:189]
	v_pk_mul_f32 v[14:15], v[8:9], v[38:39]
	v_mov_b32_e32 v38, v190
	v_mov_b32_e32 v39, v190
	v_pk_mul_f32 v[16:17], v[6:7], v[188:189]
	v_pk_mul_f32 v[6:7], v[12:13], v[38:39]
	v_pk_mul_f32 v[8:9], v[10:11], v[190:191]
	v_cndmask_b32_e64 v11, v24, v36, s[38:39]
	v_cndmask_b32_e64 v13, v24, v28, s[42:43]
	v_cndmask_b32_e64 v36, v25, v29, s[42:43]
	v_mov_b32_dpp v10, v11 row_ror:1 row_mask:0xf bank_mask:0xf
	v_mov_b32_dpp v12, v13 row_ror:15 row_mask:0xf bank_mask:0xf
	v_cndmask_b32_e64 v13, v25, v37, s[38:39]
	v_cndmask_b32_e64 v37, v22, v26, s[42:43]
	v_pk_mul_f32 v[4:5], v[4:5], v[38:39]
	v_mov_b32_dpp v11, v13 row_ror:1 row_mask:0xf bank_mask:0xf
	v_cndmask_b32_e64 v38, v23, v27, s[42:43]
	v_cndmask_b32_e64 v39, v18, v16, s[42:43]
	v_mov_b32_dpp v13, v36 row_ror:15 row_mask:0xf bank_mask:0xf
	v_cndmask_b32_e64 v36, v22, v34, s[38:39]
	v_pk_mul_f32 v[10:11], v[78:79], v[10:11]
	v_cndmask_b32_e64 v40, v19, v17, s[42:43]
	v_mov_b32_dpp v34, v36 row_ror:1 row_mask:0xf bank_mask:0xf
	v_pk_fma_f32 v[10:11], v[24:25], v[74:75], v[10:11]
	v_cndmask_b32_e64 v41, v20, v14, s[42:43]
	v_mov_b32_dpp v36, v37 row_ror:15 row_mask:0xf bank_mask:0xf
	v_cndmask_b32_e64 v37, v23, v35, s[38:39]
	v_pk_fma_f32 v[10:11], v[70:71], v[12:13], v[10:11]
	v_cndmask_b32_e64 v42, v21, v15, s[42:43]
	v_mov_b32_dpp v35, v37 row_ror:1 row_mask:0xf bank_mask:0xf
	v_pk_add_f32 v[10:11], v[66:67], v[10:11]
	v_pk_mul_f32 v[34:35], v[80:81], v[34:35]
	v_mov_b32_dpp v37, v38 row_ror:15 row_mask:0xf bank_mask:0xf
	v_cndmask_b32_e64 v38, v18, v32, s[38:39]
	v_mul_f32_e32 v12, 0xbfb8aa3b, v10
	v_pk_fma_f32 v[34:35], v[22:23], v[76:77], v[34:35]
	v_mov_b32_dpp v32, v38 row_ror:1 row_mask:0xf bank_mask:0xf
	v_pk_mul_f32 v[2:3], v[2:3], v[190:191]
	s_nop 0
	v_mov_b32_dpp v38, v39 row_ror:15 row_mask:0xf bank_mask:0xf
	v_cndmask_b32_e64 v39, v19, v33, s[38:39]
	s_nop 1
	v_mov_b32_dpp v33, v39 row_ror:1 row_mask:0xf bank_mask:0xf
	v_pk_mul_f32 v[32:33], v[94:95], v[32:33]
	s_nop 0
	v_mov_b32_dpp v39, v40 row_ror:15 row_mask:0xf bank_mask:0xf
	v_pk_fma_f32 v[32:33], v[18:19], v[90:91], v[32:33]
	v_cndmask_b32_e64 v40, v20, v30, s[38:39]
	v_pk_fma_f32 v[32:33], v[86:87], v[38:39], v[32:33]
	v_exp_f32_e32 v38, v12
	v_mul_f32_e32 v12, 0xbfb8aa3b, v11
	v_exp_f32_e32 v39, v12
	v_pk_fma_f32 v[12:13], v[72:73], v[36:37], v[34:35]
	v_add_f32_e32 v34, 1.0, v38
	v_rcp_f32_e32 v34, v34
	v_pk_add_f32 v[32:33], v[82:83], v[32:33]
	v_pk_add_f32 v[12:13], v[68:69], v[12:13]
	v_add_f32_e32 v35, 1.0, v39
	v_mul_f32_e32 v10, v10, v34
	v_mul_f32_e32 v10, v10, v32
	v_mul_f32_e32 v32, 0xbfb8aa3b, v12
	v_rcp_f32_e32 v35, v35
	v_exp_f32_e32 v32, v32
	v_mul_f32_e32 v34, 0xbfb8aa3b, v13
	v_exp_f32_e32 v34, v34
	v_mul_f32_e32 v11, v11, v35
	v_add_f32_e32 v32, 1.0, v32
	v_mov_b32_dpp v30, v40 row_ror:1 row_mask:0xf bank_mask:0xf
	v_mul_f32_e32 v11, v11, v33
	v_rcp_f32_e32 v32, v32
	v_mov_b32_dpp v40, v41 row_ror:15 row_mask:0xf bank_mask:0xf
	v_cndmask_b32_e64 v41, v21, v31, s[38:39]
	v_add_f32_e32 v33, 1.0, v34
	v_rcp_f32_e32 v33, v33
	v_mov_b32_dpp v31, v41 row_ror:1 row_mask:0xf bank_mask:0xf
	v_pk_mul_f32 v[30:31], v[96:97], v[30:31]
	v_cvt_pk_bf16_f32 v10, v10, v11
	v_mul_f32_e32 v11, v12, v32
	v_mov_b32_dpp v41, v42 row_ror:15 row_mask:0xf bank_mask:0xf
	v_pk_fma_f32 v[30:31], v[20:21], v[92:93], v[30:31]
	v_mul_f32_e32 v12, v13, v33
	v_pk_fma_f32 v[30:31], v[88:89], v[40:41], v[30:31]
	v_cndmask_b32_e64 v13, v28, v8, s[42:43]
	v_pk_add_f32 v[30:31], v[84:85], v[30:31]
	v_cndmask_b32_e64 v32, v17, v3, s[42:43]
	v_mul_f32_e32 v11, v11, v30
	v_mul_f32_e32 v12, v12, v31
	v_cvt_pk_bf16_f32 v11, v11, v12
	global_store_dwordx2 v[186:187], v[10:11], off offset:8
	v_cndmask_b32_e64 v11, v28, v24, s[38:39]
	v_cndmask_b32_e64 v24, v29, v9, s[42:43]
	s_nop 0
	v_mov_b32_dpp v10, v11 row_ror:1 row_mask:0xf bank_mask:0xf
	v_mov_b32_dpp v12, v13 row_ror:15 row_mask:0xf bank_mask:0xf
	v_cndmask_b32_e64 v13, v29, v25, s[38:39]
	v_cndmask_b32_e64 v25, v26, v6, s[42:43]
	v_cndmask_b32_e64 v30, v27, v7, s[42:43]
	v_mov_b32_dpp v11, v13 row_ror:1 row_mask:0xf bank_mask:0xf
; __device__ __forceinline__ unsigned cvt_pk_bf16(float lo, float hi) { unsigned r; asm volatile("v_cvt_pk_bf16_f32 %0, %1, %2" : "=v"(r) : "v"(lo), "v"(hi)); return r; }
;     __device__ __forceinline__ void operator()(f32x4 (&acc)[2][2][4][2], const Unit& u, int wr, int wc, int fr, int fq) const {
;     ...
;                     f32x4 cv[2];
; #pragma unroll
;                     for (int bj = 0; bj < 2; ++bj) {
;                         const f32x4 cur = acc[ai][bj][m][n], lo = acc[ai][bj][m > 0 ? m - 1 : 0][n], hi = acc[ai][bj][m < 3 ? m + 1 : 3][n];
;                         f32x4 pv, nv;
; #pragma unroll
;                         for (int idx = 0; idx < 4; ++idx) {
;                             const float y = (fr == 15) ? lo[idx] : cur[idx], z = (fr == 0) ? hi[idx] : cur[idx];
;                             pv[idx] = __int_as_float(__builtin_amdgcn_update_dpp(0, __float_as_int(y), 0x121, 0xf, 0xf, false));
;                             nv[idx] = __int_as_float(__builtin_amdgcn_update_dpp(0, __float_as_int(z), 0x12f, 0xf, 0xf, false));
;                         }
;                         cv[bj] = kc[bj][0] * pv + kc[bj][1] * cur + kc[bj][2] * nv + bc[bj];
;                     }
;                     const int row = row0 + ai * HALF + m * 16;
;                     const bool edge = (m == 0 && fr == 0) || (m == 3 && fr == 15);
;                     if (!edge) { const f32x4 gt = cv[0], vl = cv[1];
;                         u32x2 w; w.x = cvt_pk_bf16(gt[0] * sigmoid_f(gt[0]) * vl[0], gt[1] * sigmoid_f(gt[1]) * vl[1]); w.y = cvt_pk_bf16(gt[2] * sigmoid_f(gt[2]) * vl[2], gt[3] * sigmoid_f(gt[3]) * vl[3]);
;                         *(u32x2*)(ACT + (size_t)row * FF + j4) = w; }
;                     if (m == 0 && fr < 2) {
; #pragma unroll
;                         for (int bj = 0; bj < 2; ++bj) { const f32x4 v = acc[ai][bj][0][n]; u32x2 w; w.x = cvt_pk_bf16(v[0], v[1]); w.y = cvt_pk_bf16(v[2], v[3]); *(u32x2*)(RAW + ((size_t)(grp * 4 + fr)) * NUP + bj * FF + j4) = w; } }
;                     if (m == 3 && fr >= 14) {
; #pragma unroll
;                         for (int bj = 0; bj < 2; ++bj) { const f32x4 v = acc[ai][bj][3][n]; u32x2 w; w.x = cvt_pk_bf16(v[0], v[1]); w.y = cvt_pk_bf16(v[2], v[3]); *(u32x2*)(RAW + ((size_t)(grp * 4 + 2 + (fr - 14))) * NUP + bj * FF + j4) = w; } }
	v_cndmask_b32_e64 v31, v16, v2, s[42:43]
	v_pk_mul_f32 v[10:11], v[78:79], v[10:11]
	v_mov_b32_dpp v13, v24 row_ror:15 row_mask:0xf bank_mask:0xf
	v_cndmask_b32_e64 v24, v26, v22, s[38:39]
	v_pk_fma_f32 v[10:11], v[28:29], v[74:75], v[10:11]
	v_cndmask_b32_e64 v33, v14, v4, s[42:43]
	v_mov_b32_dpp v22, v24 row_ror:1 row_mask:0xf bank_mask:0xf
	v_pk_fma_f32 v[10:11], v[70:71], v[12:13], v[10:11]
	v_cndmask_b32_e64 v34, v15, v5, s[42:43]
	v_mov_b32_dpp v24, v25 row_ror:15 row_mask:0xf bank_mask:0xf
	v_cndmask_b32_e64 v25, v27, v23, s[38:39]
	v_pk_add_f32 v[10:11], v[66:67], v[10:11]
	s_nop 0
	v_mov_b32_dpp v23, v25 row_ror:1 row_mask:0xf bank_mask:0xf
	v_mul_f32_e32 v12, 0xbfb8aa3b, v10
	v_pk_mul_f32 v[22:23], v[80:81], v[22:23]
	v_mov_b32_dpp v25, v30 row_ror:15 row_mask:0xf bank_mask:0xf
	v_cndmask_b32_e64 v30, v16, v18, s[38:39]
	v_pk_fma_f32 v[22:23], v[26:27], v[76:77], v[22:23]
	s_nop 0
	v_mov_b32_dpp v18, v30 row_ror:1 row_mask:0xf bank_mask:0xf
	s_nop 1
	v_mov_b32_dpp v30, v31 row_ror:15 row_mask:0xf bank_mask:0xf
	v_cndmask_b32_e64 v31, v17, v19, s[38:39]
	s_nop 1
	v_mov_b32_dpp v19, v31 row_ror:1 row_mask:0xf bank_mask:0xf
	v_pk_mul_f32 v[18:19], v[94:95], v[18:19]
	s_nop 0
	v_mov_b32_dpp v31, v32 row_ror:15 row_mask:0xf bank_mask:0xf
	v_pk_fma_f32 v[18:19], v[16:17], v[90:91], v[18:19]
	v_cndmask_b32_e64 v32, v14, v20, s[38:39]
	v_pk_fma_f32 v[18:19], v[86:87], v[30:31], v[18:19]
	v_exp_f32_e32 v30, v12
	v_mul_f32_e32 v12, 0xbfb8aa3b, v11
	v_exp_f32_e32 v31, v12
	v_pk_fma_f32 v[12:13], v[72:73], v[24:25], v[22:23]
	v_add_f32_e32 v22, 1.0, v30
	v_rcp_f32_e32 v22, v22
	v_pk_add_f32 v[18:19], v[82:83], v[18:19]
	v_pk_add_f32 v[12:13], v[68:69], v[12:13]
	v_add_f32_e32 v23, 1.0, v31
	v_mul_f32_e32 v10, v10, v22
	v_mul_f32_e32 v10, v10, v18
	v_mul_f32_e32 v18, 0xbfb8aa3b, v12
	v_rcp_f32_e32 v23, v23
	v_exp_f32_e32 v18, v18
	v_mul_f32_e32 v22, 0xbfb8aa3b, v13
	v_exp_f32_e32 v22, v22
	v_mul_f32_e32 v11, v11, v23
	v_add_f32_e32 v18, 1.0, v18
	v_mov_b32_dpp v20, v32 row_ror:1 row_mask:0xf bank_mask:0xf
	v_mul_f32_e32 v11, v11, v19
	v_rcp_f32_e32 v18, v18
	v_mov_b32_dpp v32, v33 row_ror:15 row_mask:0xf bank_mask:0xf
	v_cndmask_b32_e64 v33, v15, v21, s[38:39]
	v_add_f32_e32 v19, 1.0, v22
	v_rcp_f32_e32 v19, v19
	v_mov_b32_dpp v21, v33 row_ror:1 row_mask:0xf bank_mask:0xf
	v_pk_mul_f32 v[20:21], v[96:97], v[20:21]
	v_cvt_pk_bf16_f32 v10, v10, v11
	v_mul_f32_e32 v11, v12, v18
	v_mov_b32_dpp v33, v34 row_ror:15 row_mask:0xf bank_mask:0xf
	v_pk_fma_f32 v[20:21], v[14:15], v[92:93], v[20:21]
	v_mul_f32_e32 v12, v13, v19
	v_pk_fma_f32 v[20:21], v[88:89], v[32:33], v[20:21]
	v_pk_add_f32 v[20:21], v[84:85], v[20:21]
	v_mul_f32_e32 v11, v11, v20
	v_mul_f32_e32 v12, v12, v21
	v_cvt_pk_bf16_f32 v11, v11, v12
	global_store_dwordx2 v[184:185], v[10:11], off offset:8
	v_cndmask_b32_e64 v10, v8, v28, s[38:39]
	v_cndmask_b32_e64 v11, v7, v27, s[38:39]
	s_nop 0
	v_mov_b32_dpp v18, v10 row_ror:1 row_mask:0xf bank_mask:0xf
	v_cndmask_b32_e64 v10, v9, v29, s[38:39]
	v_cndmask_b32_e64 v16, v2, v16, s[38:39]
	s_nop 0
	v_mov_b32_dpp v19, v10 row_ror:1 row_mask:0xf bank_mask:0xf
	v_cndmask_b32_e64 v10, v6, v26, s[38:39]
	v_cndmask_b32_e64 v17, v3, v17, s[38:39]
	v_cndmask_b32_e64 v14, v4, v14, s[38:39]
	v_cndmask_b32_e64 v15, v5, v15, s[38:39]
	v_mov_b32_dpp v20, v10 row_ror:1 row_mask:0xf bank_mask:0xf
	v_mov_b32_dpp v21, v11 row_ror:1 row_mask:0xf bank_mask:0xf
	v_mov_b32_dpp v22, v16 row_ror:1 row_mask:0xf bank_mask:0xf
	v_mov_b32_dpp v23, v17 row_ror:1 row_mask:0xf bank_mask:0xf
	v_mov_b32_dpp v24, v14 row_ror:1 row_mask:0xf bank_mask:0xf
	v_mov_b32_dpp v25, v15 row_ror:1 row_mask:0xf bank_mask:0xf
	v_mov_b32_dpp v12, v8 row_ror:15 row_mask:0xf bank_mask:0xf
	v_mov_b32_dpp v13, v9 row_ror:15 row_mask:0xf bank_mask:0xf
	v_mov_b32_dpp v10, v6 row_ror:15 row_mask:0xf bank_mask:0xf
	v_mov_b32_dpp v11, v7 row_ror:15 row_mask:0xf bank_mask:0xf
	v_mov_b32_dpp v16, v2 row_ror:15 row_mask:0xf bank_mask:0xf
	v_mov_b32_dpp v17, v3 row_ror:15 row_mask:0xf bank_mask:0xf
	v_mov_b32_dpp v14, v4 row_ror:15 row_mask:0xf bank_mask:0xf
	v_mov_b32_dpp v15, v5 row_ror:15 row_mask:0xf bank_mask:0xf
	s_and_saveexec_b64 s[12:13], s[40:41]
	s_cbranch_execnz .LBB0_786
	s_or_b64 exec, exec, s[12:13]
	s_and_saveexec_b64 s[12:13], s[48:49]
	s_cbranch_execnz .LBB0_787
